# per-row stat reductions in the three store-only GEMM epilogues: xor-16/xor-32 butterfly steps via v_permlane16_swap/v_permlane32_swap (VALU) instead of ds_bpermute round trips
# baseline (speedup 1.0000x reference)
; __device__ __forceinline__ unsigned pk2(float lo, float hi) { return pg8::cvt_pk_bf16(lo, hi); }
;     __device__ __forceinline__ void operator()(const f32x4 (&acc)[2][2][4][2], const pg8::Unit& u, int wr, int wc, int fr, int fq) const {
;         const int row0 = u.pm * 256 + wr * 64 + fr, col0 = u.pn * 256 + wc * 32 + 8 * fq;
;         const int Rt = rowbase + u.pm * 256;
;         const float* bp = bias + (size_t)(Rt < TL ? (Rt >> 13) : 8) * FF2 + col0;
;         f32x4 bv[2][2];
; #pragma unroll
;         for (int bj = 0; bj < 2; ++bj) { bv[bj][0] = *(const f32x4*)(bp + bj * 128); bv[bj][1] = *(const f32x4*)(bp + bj * 128 + 4); }
; #pragma unroll
;         for (int ai = 0; ai < 2; ++ai)
; #pragma unroll
;             for (int m = 0; m < 4; ++m) { const int r = row0 + ai * 128 + m * 16, Rg = rowbase + r;
;                 const f32x4 q = *(const f32x4*)(stat + (size_t)Rg * 16 + fq * 4);
;                 float ssq = (q[0] + q[1]) + (q[2] + q[3]); ssq += __shfl_xor(ssq, 16); ssq += __shfl_xor(ssq, 32);
;                 const float rstd = rsqrtf(ssq * (1.f / DM) + 1e-6f);
;                 bf16_t* rowp = O + (size_t)r * ldc + col0;
; #pragma unroll
;                 for (int bj = 0; bj < 2; ++bj) { const f32x4 v0 = acc[ai][bj][m][0] * rstd + bv[bj][0], v1 = acc[ai][bj][m][1] * rstd + bv[bj][1];
;                     u32x4 w; w.x = pk2(v0[0], v0[1]); w.y = pk2(v0[2], v0[3]); w.z = pk2(v1[0], v1[1]); w.w = pk2(v1[2], v1[3]);
;                     *(u32x4*)(rowp + bj * 128) = w; } }
.LBB0_165:
	v_and_b32_e32 v160, 64, v228
	v_xor_b32_e32 v159, 16, v228
	v_add_u32_e32 v160, 64, v160
	s_lshl_b32 s10, s56, 8
	v_cmp_lt_i32_e32 vcc, v159, v160
	s_min_i32 s11, s10, 0x8000
	s_add_i32 s11, s11, 0x8000
	v_cndmask_b32_e32 v159, v228, v159, vcc
	v_lshlrev_b32_e32 v186, 2, v159
	v_xor_b32_e32 v159, 32, v228
	s_ashr_i32 s11, s11, 13
	v_cmp_lt_i32_e32 vcc, v159, v160
	s_mul_i32 s34, s11, 0x1600
	v_add_u32_e32 v158, s10, v182
	v_cndmask_b32_e32 v159, v228, v159, vcc
	s_ashr_i32 s35, s34, 31
	v_lshlrev_b32_e32 v187, 2, v159
	v_ashrrev_i32_e32 v159, 31, v158
	s_lshl_b64 s[34:35], s[34:35], 2
	v_lshlrev_b64 v[160:161], 6, v[158:159]
	v_lshl_or_b32 v176, s55, 8, v184
	s_add_u32 s34, s0, s34
	v_lshl_add_u64 v[178:179], v[152:153], 0, v[160:161]
	s_mov_b32 s10, 0x200000
	s_addc_u32 s35, s51, s35
	v_ashrrev_i32_e32 v177, 31, v176
	v_add_co_u32_e32 v180, vcc, s10, v178
	v_lshl_add_u64 v[94:95], v[176:177], 2, s[34:35]
	s_nop 0
	v_addc_co_u32_e32 v181, vcc, 0, v179, vcc
	v_lshlrev_b32_e32 v195, 2, v184
	v_add_u32_e32 v195, 0x24010, v195
	ds_read_b128 v[98:101], v195 offset:16
	ds_read_b128 v[102:105], v195
	ds_read_b128 v[90:93], v195 offset:528
	ds_read_b128 v[94:97], v195 offset:512
	v_lshlrev_b64 v[176:177], 1, v[176:177]
	v_lshlrev_b32_e32 v194, 6, v182
	v_and_b32_e32 v195, 48, v163
	v_add_u32_e32 v194, v194, v195
	v_add_u32_e32 v194, 0x20010, v194
	ds_read_b128 v[188:191], v194
	ds_read_b128 v[196:199], v194 offset:1024
	ds_read_b128 v[200:203], v194 offset:2048
	ds_read_b128 v[204:207], v194 offset:3072
	ds_read_b128 v[208:211], v194 offset:8192
	ds_read_b128 v[212:215], v194 offset:9216
	ds_read_b128 v[216:219], v194 offset:10240
	ds_read_b128 v[220:223], v194 offset:11264
	s_mov_b32 s10, 0x202000
	s_mov_b64 s[44:45], -1
	s_waitcnt vmcnt(0) lgkmcnt(0)
	s_barrier
	v_lshlrev_b32_e32 v244, 4, v228
	v_readfirstlane_b32 s98, v163
	v_readfirstlane_b32 s100, v152
	v_readfirstlane_b32 s101, v153
	s_lshl_b32 s98, s98, 5
	s_lshl_b32 s99, 0x8000, 6
	s_lshl_b32 s32, s71, 14
	s_add_i32 s99, s99, s32
	s_add_i32 s99, s99, s98
	s_add_u32 s100, s100, s99
	s_addc_u32 s101, s101, 0
	s_add_i32 m0, s98, 0x20010
	s_nop 0
	global_load_lds_dwordx4 v244, s[100:101]
	global_load_lds_dwordx4 v244, s[100:101] offset:1024
	s_lshl_b32 s99, s71, 8
	s_add_i32 s99, s99, 0x8000
	s_min_i32 s99, s99, 0x10000
	s_ashr_i32 s99, s99, 13
	s_mulk_i32 s99, 0x1600
	s_lshl_b32 s99, s99, 2
	s_lshl_b32 s32, s73, 10
	s_add_i32 s99, s99, s32
	s_add_u32 s100, s0, s99
	s_addc_u32 s101, s51, 0
	s_mov_b32 m0, 0x24010
	s_nop 0
	global_load_lds_dwordx4 v244, s[100:101]
	v_mov_b32_e32 v160, v189
	v_mov_b32_e32 v161, v190
	v_mov_b32_e32 v189, v191
	v_pk_add_f32 v[160:161], v[160:161], v[188:189]
	s_nop 0
	v_add_f32_e32 v159, v160, v161
	v_mov_b32_e32 v160, v159
	s_nop 1
	v_permlane16_swap_b32_e32 v159, v160
	s_waitcnt lgkmcnt(0)
	v_add_f32_e32 v159, v159, v160
	v_mov_b32_e32 v160, v159
	s_nop 1
	v_permlane32_swap_b32_e32 v159, v160
	s_waitcnt lgkmcnt(0)
	v_add_f32_e32 v159, v159, v160
	v_fmamk_f32 v159, v159, 0x3a800000, v162
	v_cmp_gt_f32_e32 vcc, s82, v159
	v_mul_f32_e32 v160, 0x4b800000, v159
	s_nop 0
	v_cndmask_b32_e32 v159, v159, v160, vcc
	v_rsq_f32_e32 v159, v159
	s_nop 0
	v_mul_f32_e32 v160, 0x45800000, v159
	v_cndmask_b32_e32 v188, v159, v160, vcc
	v_mov_b64_e32 v[160:161], s[20:21]
	v_mad_i64_i32 v[190:191], s[34:35], v158, s83, v[160:161]
	v_pk_fma_f32 v[144:145], v[144:145], v[188:189], v[104:105] op_sel_hi:[1,0,1]
	v_pk_fma_f32 v[142:143], v[142:143], v[188:189], v[102:103] op_sel_hi:[1,0,1]
	v_pk_fma_f32 v[192:193], v[140:141], v[188:189], v[100:101] op_sel_hi:[1,0,1]
	v_pk_fma_f32 v[140:141], v[138:139], v[188:189], v[98:99] op_sel_hi:[1,0,1]
	v_lshl_add_u64 v[190:191], v[190:191], 0, v[176:177]
	v_cvt_pk_bf16_f32 v138, v142, v143
	v_cvt_pk_bf16_f32 v139, v144, v145
	v_cvt_pk_bf16_f32 v140, v140, v141
	v_cvt_pk_bf16_f32 v141, v192, v193
	global_store_dwordx4 v[190:191], v[138:141], off
	v_pk_fma_f32 v[136:137], v[136:137], v[188:189], v[96:97] op_sel_hi:[1,0,1]
	v_pk_fma_f32 v[134:135], v[134:135], v[188:189], v[94:95] op_sel_hi:[1,0,1]
	v_pk_fma_f32 v[138:139], v[132:133], v[188:189], v[92:93] op_sel_hi:[1,0,1]
	v_pk_fma_f32 v[132:133], v[130:131], v[188:189], v[90:91] op_sel_hi:[1,0,1]
	v_cvt_pk_bf16_f32 v130, v134, v135
	v_cvt_pk_bf16_f32 v131, v136, v137
	v_cvt_pk_bf16_f32 v132, v132, v133
	v_cvt_pk_bf16_f32 v133, v138, v139
	global_store_dwordx4 v[190:191], v[130:133], off offset:256
	v_or_b32_e32 v136, 16, v158
	s_nop 1
	v_add_f32_e32 v130, v196, v197
	v_add_f32_e32 v131, v198, v199
	v_mad_i64_i32 v[132:133], s[34:35], v136, s83, v[160:161]
	v_add_f32_e32 v130, v130, v131
	v_mov_b32_e32 v131, v130
	s_nop 1
	v_permlane16_swap_b32_e32 v130, v131
	v_lshl_add_u64 v[132:133], v[132:133], 0, v[176:177]
	s_waitcnt lgkmcnt(0)
	v_add_f32_e32 v130, v130, v131
	v_mov_b32_e32 v131, v130
	s_nop 1
	v_permlane32_swap_b32_e32 v130, v131
	s_waitcnt lgkmcnt(0)
; __device__ __forceinline__ unsigned pk2(float lo, float hi) { return pg8::cvt_pk_bf16(lo, hi); }
;     __device__ __forceinline__ void operator()(const f32x4 (&acc)[2][2][4][2], const pg8::Unit& u, int wr, int wc, int fr, int fq) const {
;     ...
;             for (int m = 0; m < 4; ++m) { const int r = row0 + ai * 128 + m * 16, Rg = rowbase + r;
;                 const f32x4 q = *(const f32x4*)(stat + (size_t)Rg * 16 + fq * 4);
;                 float ssq = (q[0] + q[1]) + (q[2] + q[3]); ssq += __shfl_xor(ssq, 16); ssq += __shfl_xor(ssq, 32);
;                 const float rstd = rsqrtf(ssq * (1.f / DM) + 1e-6f);
;                 bf16_t* rowp = O + (size_t)r * ldc + col0;
; #pragma unroll
;                 for (int bj = 0; bj < 2; ++bj) { const f32x4 v0 = acc[ai][bj][m][0] * rstd + bv[bj][0], v1 = acc[ai][bj][m][1] * rstd + bv[bj][1];
;                     u32x4 w; w.x = pk2(v0[0], v0[1]); w.y = pk2(v0[2], v0[3]); w.z = pk2(v1[0], v1[1]); w.w = pk2(v1[2], v1[3]);
;                     *(u32x4*)(rowp + bj * 128) = w; } }
	v_add_f32_e32 v130, v130, v131
	v_fmamk_f32 v130, v130, 0x3a800000, v162
	v_cmp_gt_f32_e32 vcc, s82, v130
	v_mul_f32_e32 v131, 0x4b800000, v130
	s_nop 0
	v_cndmask_b32_e32 v130, v130, v131, vcc
	v_rsq_f32_e32 v130, v130
	s_nop 0
	v_mul_f32_e32 v131, 0x45800000, v130
	v_cndmask_b32_e32 v130, v130, v131, vcc
	v_pk_fma_f32 v[128:129], v[128:129], v[130:131], v[104:105] op_sel_hi:[1,0,1]
	v_pk_fma_f32 v[126:127], v[126:127], v[130:131], v[102:103] op_sel_hi:[1,0,1]
	v_pk_fma_f32 v[134:135], v[124:125], v[130:131], v[100:101] op_sel_hi:[1,0,1]
	v_pk_fma_f32 v[124:125], v[122:123], v[130:131], v[98:99] op_sel_hi:[1,0,1]
	v_cvt_pk_bf16_f32 v122, v126, v127
	v_cvt_pk_bf16_f32 v123, v128, v129
	v_cvt_pk_bf16_f32 v124, v124, v125
	v_cvt_pk_bf16_f32 v125, v134, v135
	global_store_dwordx4 v[132:133], v[122:125], off
	v_pk_fma_f32 v[120:121], v[120:121], v[130:131], v[96:97] op_sel_hi:[1,0,1]
	v_pk_fma_f32 v[118:119], v[118:119], v[130:131], v[94:95] op_sel_hi:[1,0,1]
	v_pk_fma_f32 v[122:123], v[116:117], v[130:131], v[92:93] op_sel_hi:[1,0,1]
	v_pk_fma_f32 v[116:117], v[114:115], v[130:131], v[90:91] op_sel_hi:[1,0,1]
	v_cvt_pk_bf16_f32 v114, v118, v119
	v_cvt_pk_bf16_f32 v115, v120, v121
	v_cvt_pk_bf16_f32 v116, v116, v117
	v_cvt_pk_bf16_f32 v117, v122, v123
	global_store_dwordx4 v[132:133], v[114:117], off offset:256
	v_or_b32_e32 v120, 32, v158
	s_nop 1
	v_add_f32_e32 v114, v200, v201
	v_add_f32_e32 v115, v202, v203
	v_mad_i64_i32 v[116:117], s[34:35], v120, s83, v[160:161]
	v_add_f32_e32 v114, v114, v115
	v_mov_b32_e32 v115, v114
	s_nop 1
	v_permlane16_swap_b32_e32 v114, v115
	v_lshl_add_u64 v[116:117], v[116:117], 0, v[176:177]
	s_waitcnt lgkmcnt(0)
	v_add_f32_e32 v114, v114, v115
	v_mov_b32_e32 v115, v114
	s_nop 1
	v_permlane32_swap_b32_e32 v114, v115
	s_waitcnt lgkmcnt(0)
	v_add_f32_e32 v114, v114, v115
	v_fmamk_f32 v114, v114, 0x3a800000, v162
	v_cmp_gt_f32_e32 vcc, s82, v114
	v_mul_f32_e32 v115, 0x4b800000, v114
	s_nop 0
	v_cndmask_b32_e32 v114, v114, v115, vcc
	v_rsq_f32_e32 v114, v114
	s_nop 0
	v_mul_f32_e32 v115, 0x45800000, v114
	v_cndmask_b32_e32 v114, v114, v115, vcc
	v_pk_fma_f32 v[112:113], v[112:113], v[114:115], v[104:105] op_sel_hi:[1,0,1]
	v_pk_fma_f32 v[110:111], v[110:111], v[114:115], v[102:103] op_sel_hi:[1,0,1]
	v_pk_fma_f32 v[118:119], v[108:109], v[114:115], v[100:101] op_sel_hi:[1,0,1]
	v_pk_fma_f32 v[108:109], v[106:107], v[114:115], v[98:99] op_sel_hi:[1,0,1]
	v_cvt_pk_bf16_f32 v106, v110, v111
	v_cvt_pk_bf16_f32 v107, v112, v113
	v_cvt_pk_bf16_f32 v108, v108, v109
	v_cvt_pk_bf16_f32 v109, v118, v119
	global_store_dwordx4 v[116:117], v[106:109], off
	v_pk_fma_f32 v[88:89], v[88:89], v[114:115], v[96:97] op_sel_hi:[1,0,1]
	v_pk_fma_f32 v[86:87], v[86:87], v[114:115], v[94:95] op_sel_hi:[1,0,1]
	v_pk_fma_f32 v[106:107], v[84:85], v[114:115], v[92:93] op_sel_hi:[1,0,1]
	v_pk_fma_f32 v[84:85], v[82:83], v[114:115], v[90:91] op_sel_hi:[1,0,1]
	v_cvt_pk_bf16_f32 v82, v86, v87
	v_cvt_pk_bf16_f32 v83, v88, v89
	v_cvt_pk_bf16_f32 v84, v84, v85
	v_cvt_pk_bf16_f32 v85, v106, v107
	global_store_dwordx4 v[116:117], v[82:85], off offset:256
	v_or_b32_e32 v88, 48, v158
	s_nop 1
	v_add_f32_e32 v82, v204, v205
	v_add_f32_e32 v83, v206, v207
	v_mad_i64_i32 v[84:85], s[34:35], v88, s83, v[160:161]
	v_add_f32_e32 v82, v82, v83
	v_mov_b32_e32 v83, v82
	s_nop 1
	v_permlane16_swap_b32_e32 v82, v83
	v_lshl_add_u64 v[84:85], v[84:85], 0, v[176:177]
	s_waitcnt lgkmcnt(0)
	v_add_f32_e32 v82, v82, v83
	v_mov_b32_e32 v83, v82
	s_nop 1
	v_permlane32_swap_b32_e32 v82, v83
	s_waitcnt lgkmcnt(0)
	v_add_f32_e32 v82, v82, v83
	v_fmamk_f32 v82, v82, 0x3a800000, v162
	v_cmp_gt_f32_e32 vcc, s82, v82
	v_mul_f32_e32 v83, 0x4b800000, v82
	s_nop 0
	v_cndmask_b32_e32 v82, v82, v83, vcc
	v_rsq_f32_e32 v82, v82
	s_nop 0
	v_mul_f32_e32 v83, 0x45800000, v82
	v_cndmask_b32_e32 v82, v82, v83, vcc
	v_pk_fma_f32 v[80:81], v[80:81], v[82:83], v[104:105] op_sel_hi:[1,0,1]
	v_pk_fma_f32 v[78:79], v[78:79], v[82:83], v[102:103] op_sel_hi:[1,0,1]
	v_pk_fma_f32 v[86:87], v[76:77], v[82:83], v[100:101] op_sel_hi:[1,0,1]
	v_pk_fma_f32 v[76:77], v[74:75], v[82:83], v[98:99] op_sel_hi:[1,0,1]
	v_cvt_pk_bf16_f32 v74, v78, v79
	v_cvt_pk_bf16_f32 v75, v80, v81
	v_cvt_pk_bf16_f32 v76, v76, v77
	v_cvt_pk_bf16_f32 v77, v86, v87
	global_store_dwordx4 v[84:85], v[74:77], off
	v_pk_fma_f32 v[72:73], v[72:73], v[82:83], v[96:97] op_sel_hi:[1,0,1]
	v_pk_fma_f32 v[70:71], v[70:71], v[82:83], v[94:95] op_sel_hi:[1,0,1]
	v_pk_fma_f32 v[74:75], v[68:69], v[82:83], v[92:93] op_sel_hi:[1,0,1]
	v_pk_fma_f32 v[68:69], v[66:67], v[82:83], v[90:91] op_sel_hi:[1,0,1]
	v_cvt_pk_bf16_f32 v66, v70, v71
	v_cvt_pk_bf16_f32 v67, v72, v73
	v_cvt_pk_bf16_f32 v68, v68, v69
	v_cvt_pk_bf16_f32 v69, v74, v75
	global_store_dwordx4 v[84:85], v[66:69], off offset:256
	v_add_u32_e32 v74, 0x80, v158
	s_nop 0
	v_add_co_u32_e32 v66, vcc, s10, v178
	s_nop 1
	v_addc_co_u32_e32 v67, vcc, 0, v179, vcc
	s_nop 1
	v_add_f32_e32 v68, v208, v209
	v_add_f32_e32 v69, v210, v211
	v_mad_i64_i32 v[70:71], s[34:35], v74, s83, v[160:161]
	v_add_f32_e32 v68, v68, v69
	v_mov_b32_e32 v69, v68
	s_nop 1
	v_permlane16_swap_b32_e32 v68, v69
	v_lshl_add_u64 v[70:71], v[70:71], 0, v[176:177]
	s_waitcnt lgkmcnt(0)
	v_add_f32_e32 v68, v68, v69
	v_mov_b32_e32 v69, v68
	s_nop 1
	v_permlane32_swap_b32_e32 v68, v69
	s_waitcnt lgkmcnt(0)
; #define PG8_BAR __builtin_amdgcn_s_barrier()
; __device__ __forceinline__ unsigned pk2(float lo, float hi) { return pg8::cvt_pk_bf16(lo, hi); }
; template <class Epi, class Sched, bool ALIGN_EPI = false, bool SP2 = false>
; __device__ __forceinline__ void gemm_phase(PG8_LAS unsigned char* lds, const Gemm g, const Sched& S, const Epi& E) {
;     ...
;         if (!has_next) break;
; #pragma unroll
;         for (int a = 0; a < 2; ++a)
; #pragma unroll
;             for (int b = 0; b < 2; ++b)
; #pragma unroll
;                 for (int m = 0; m < 4; ++m)
; #pragma unroll
;                     for (int n = 0; n < 2; ++n) acc[a][b][m][n] = (f32x4){0.f, 0.f, 0.f, 0.f};
;         cur = nxt; cA = nA; cB = nB; ++ui;
;         if constexpr (ALIGN_EPI) { if (wr == 1) PG8_BAR; }
;     __device__ __forceinline__ void operator()(const f32x4 (&acc)[2][2][4][2], const pg8::Unit& u, int wr, int wc, int fr, int fq) const {
;     ...
;             for (int m = 0; m < 4; ++m) { const int r = row0 + ai * 128 + m * 16, Rg = rowbase + r;
;                 const f32x4 q = *(const f32x4*)(stat + (size_t)Rg * 16 + fq * 4);
;                 float ssq = (q[0] + q[1]) + (q[2] + q[3]); ssq += __shfl_xor(ssq, 16); ssq += __shfl_xor(ssq, 32);
;                 const float rstd = rsqrtf(ssq * (1.f / DM) + 1e-6f);
;                 bf16_t* rowp = O + (size_t)r * ldc + col0;
; #pragma unroll
;                 for (int bj = 0; bj < 2; ++bj) { const f32x4 v0 = acc[ai][bj][m][0] * rstd + bv[bj][0], v1 = acc[ai][bj][m][1] * rstd + bv[bj][1];
;                     u32x4 w; w.x = pk2(v0[0], v0[1]); w.y = pk2(v0[2], v0[3]); w.z = pk2(v1[0], v1[1]); w.w = pk2(v1[2], v1[3]);
;                     *(u32x4*)(rowp + bj * 128) = w; } }
	v_add_f32_e32 v68, v68, v69
	v_fmamk_f32 v68, v68, 0x3a800000, v162
	v_cmp_gt_f32_e32 vcc, s82, v68
	v_mul_f32_e32 v69, 0x4b800000, v68
	s_nop 0
	v_cndmask_b32_e32 v68, v68, v69, vcc
	v_rsq_f32_e32 v68, v68
	s_nop 0
	v_mul_f32_e32 v69, 0x45800000, v68
	v_cndmask_b32_e32 v68, v68, v69, vcc
	v_pk_fma_f32 v[64:65], v[64:65], v[68:69], v[104:105] op_sel_hi:[1,0,1]
	v_pk_fma_f32 v[62:63], v[62:63], v[68:69], v[102:103] op_sel_hi:[1,0,1]
	v_pk_fma_f32 v[72:73], v[60:61], v[68:69], v[100:101] op_sel_hi:[1,0,1]
	v_pk_fma_f32 v[60:61], v[58:59], v[68:69], v[98:99] op_sel_hi:[1,0,1]
	v_cvt_pk_bf16_f32 v58, v62, v63
	v_cvt_pk_bf16_f32 v59, v64, v65
	v_cvt_pk_bf16_f32 v60, v60, v61
	v_cvt_pk_bf16_f32 v61, v72, v73
	global_store_dwordx4 v[70:71], v[58:61], off
	v_pk_fma_f32 v[56:57], v[56:57], v[68:69], v[96:97] op_sel_hi:[1,0,1]
	v_pk_fma_f32 v[54:55], v[54:55], v[68:69], v[94:95] op_sel_hi:[1,0,1]
	v_pk_fma_f32 v[58:59], v[52:53], v[68:69], v[92:93] op_sel_hi:[1,0,1]
	v_pk_fma_f32 v[52:53], v[50:51], v[68:69], v[90:91] op_sel_hi:[1,0,1]
	v_cvt_pk_bf16_f32 v50, v54, v55
	v_cvt_pk_bf16_f32 v51, v56, v57
	v_cvt_pk_bf16_f32 v52, v52, v53
	v_cvt_pk_bf16_f32 v53, v58, v59
	global_store_dwordx4 v[70:71], v[50:53], off offset:256
	v_add_u32_e32 v56, 0x90, v158
	s_nop 1
	v_add_f32_e32 v50, v212, v213
	v_add_f32_e32 v51, v214, v215
	v_mad_i64_i32 v[52:53], s[34:35], v56, s83, v[160:161]
	v_add_f32_e32 v50, v50, v51
	v_mov_b32_e32 v51, v50
	s_nop 1
	v_permlane16_swap_b32_e32 v50, v51
	v_lshl_add_u64 v[52:53], v[52:53], 0, v[176:177]
	s_waitcnt lgkmcnt(0)
	v_add_f32_e32 v50, v50, v51
	v_mov_b32_e32 v51, v50
	s_nop 1
	v_permlane32_swap_b32_e32 v50, v51
	s_waitcnt lgkmcnt(0)
	v_add_f32_e32 v50, v50, v51
	v_fmamk_f32 v50, v50, 0x3a800000, v162
	v_cmp_gt_f32_e32 vcc, s82, v50
	v_mul_f32_e32 v51, 0x4b800000, v50
	s_nop 0
	v_cndmask_b32_e32 v50, v50, v51, vcc
	v_rsq_f32_e32 v50, v50
	s_nop 0
	v_mul_f32_e32 v51, 0x45800000, v50
	v_cndmask_b32_e32 v50, v50, v51, vcc
	v_pk_fma_f32 v[48:49], v[48:49], v[50:51], v[104:105] op_sel_hi:[1,0,1]
	v_pk_fma_f32 v[46:47], v[46:47], v[50:51], v[102:103] op_sel_hi:[1,0,1]
	v_pk_fma_f32 v[54:55], v[44:45], v[50:51], v[100:101] op_sel_hi:[1,0,1]
	v_pk_fma_f32 v[44:45], v[42:43], v[50:51], v[98:99] op_sel_hi:[1,0,1]
	v_cvt_pk_bf16_f32 v42, v46, v47
	v_cvt_pk_bf16_f32 v43, v48, v49
	v_cvt_pk_bf16_f32 v44, v44, v45
	v_cvt_pk_bf16_f32 v45, v54, v55
	global_store_dwordx4 v[52:53], v[42:45], off
	v_pk_fma_f32 v[40:41], v[40:41], v[50:51], v[96:97] op_sel_hi:[1,0,1]
	v_pk_fma_f32 v[38:39], v[38:39], v[50:51], v[94:95] op_sel_hi:[1,0,1]
	v_pk_fma_f32 v[42:43], v[36:37], v[50:51], v[92:93] op_sel_hi:[1,0,1]
	v_pk_fma_f32 v[36:37], v[34:35], v[50:51], v[90:91] op_sel_hi:[1,0,1]
	v_cvt_pk_bf16_f32 v34, v38, v39
	v_cvt_pk_bf16_f32 v35, v40, v41
	v_cvt_pk_bf16_f32 v36, v36, v37
	v_cvt_pk_bf16_f32 v37, v42, v43
	global_store_dwordx4 v[52:53], v[34:37], off offset:256
	v_add_u32_e32 v40, 0xa0, v158
	s_nop 1
	v_add_f32_e32 v34, v216, v217
	v_add_f32_e32 v35, v218, v219
	v_mad_i64_i32 v[36:37], s[34:35], v40, s83, v[160:161]
	v_add_f32_e32 v34, v34, v35
	v_mov_b32_e32 v35, v34
	s_nop 1
	v_permlane16_swap_b32_e32 v34, v35
	v_lshl_add_u64 v[36:37], v[36:37], 0, v[176:177]
	s_waitcnt lgkmcnt(0)
	v_add_f32_e32 v34, v34, v35
	v_mov_b32_e32 v35, v34
	s_nop 1
	v_permlane32_swap_b32_e32 v34, v35
	s_waitcnt lgkmcnt(0)
	v_add_f32_e32 v34, v34, v35
	v_fmamk_f32 v34, v34, 0x3a800000, v162
	v_cmp_gt_f32_e32 vcc, s82, v34
	v_mul_f32_e32 v35, 0x4b800000, v34
	s_nop 0
	v_cndmask_b32_e32 v34, v34, v35, vcc
	v_rsq_f32_e32 v34, v34
	s_nop 0
	v_mul_f32_e32 v35, 0x45800000, v34
	v_cndmask_b32_e32 v34, v34, v35, vcc
	v_pk_fma_f32 v[32:33], v[32:33], v[34:35], v[104:105] op_sel_hi:[1,0,1]
	v_pk_fma_f32 v[30:31], v[30:31], v[34:35], v[102:103] op_sel_hi:[1,0,1]
	v_pk_fma_f32 v[38:39], v[28:29], v[34:35], v[100:101] op_sel_hi:[1,0,1]
	v_pk_fma_f32 v[28:29], v[26:27], v[34:35], v[98:99] op_sel_hi:[1,0,1]
	v_cvt_pk_bf16_f32 v26, v30, v31
	v_cvt_pk_bf16_f32 v27, v32, v33
	v_cvt_pk_bf16_f32 v28, v28, v29
	v_cvt_pk_bf16_f32 v29, v38, v39
	global_store_dwordx4 v[36:37], v[26:29], off
	v_pk_fma_f32 v[24:25], v[24:25], v[34:35], v[96:97] op_sel_hi:[1,0,1]
	v_pk_fma_f32 v[22:23], v[22:23], v[34:35], v[94:95] op_sel_hi:[1,0,1]
	v_pk_fma_f32 v[26:27], v[20:21], v[34:35], v[92:93] op_sel_hi:[1,0,1]
	v_pk_fma_f32 v[20:21], v[18:19], v[34:35], v[90:91] op_sel_hi:[1,0,1]
	v_cvt_pk_bf16_f32 v18, v22, v23
	v_cvt_pk_bf16_f32 v19, v24, v25
	v_cvt_pk_bf16_f32 v20, v20, v21
	v_cvt_pk_bf16_f32 v21, v26, v27
	global_store_dwordx4 v[36:37], v[18:21], off offset:256
	v_add_u32_e32 v24, 0xb0, v158
	s_nop 1
	v_add_f32_e32 v18, v220, v221
	v_add_f32_e32 v19, v222, v223
	v_mad_i64_i32 v[20:21], s[34:35], v24, s83, v[160:161]
	v_add_f32_e32 v18, v18, v19
	v_mov_b32_e32 v19, v18
	s_nop 1
	v_permlane16_swap_b32_e32 v18, v19
	v_lshl_add_u64 v[20:21], v[20:21], 0, v[176:177]
	s_waitcnt lgkmcnt(0)
	v_add_f32_e32 v18, v18, v19
	v_mov_b32_e32 v19, v18
	s_nop 1
	v_permlane32_swap_b32_e32 v18, v19
	s_waitcnt lgkmcnt(0)
	v_add_f32_e32 v18, v18, v19
	v_fmamk_f32 v18, v18, 0x3a800000, v162
	v_cmp_gt_f32_e32 vcc, s82, v18
	v_mul_f32_e32 v19, 0x4b800000, v18
	s_nop 0
	v_cndmask_b32_e32 v18, v18, v19, vcc
	v_rsq_f32_e32 v18, v18
	s_nop 0
	v_mul_f32_e32 v19, 0x45800000, v18
	v_cndmask_b32_e32 v18, v18, v19, vcc
	v_pk_fma_f32 v[16:17], v[16:17], v[18:19], v[104:105] op_sel_hi:[1,0,1]
	v_pk_fma_f32 v[14:15], v[14:15], v[18:19], v[102:103] op_sel_hi:[1,0,1]
	v_pk_fma_f32 v[22:23], v[12:13], v[18:19], v[100:101] op_sel_hi:[1,0,1]
	v_pk_fma_f32 v[12:13], v[10:11], v[18:19], v[98:99] op_sel_hi:[1,0,1]
	v_cvt_pk_bf16_f32 v10, v14, v15
	v_cvt_pk_bf16_f32 v11, v16, v17
	v_cvt_pk_bf16_f32 v12, v12, v13
	v_cvt_pk_bf16_f32 v13, v22, v23
	global_store_dwordx4 v[20:21], v[10:13], off
	v_pk_fma_f32 v[8:9], v[8:9], v[18:19], v[96:97] op_sel_hi:[1,0,1]
	v_pk_fma_f32 v[6:7], v[6:7], v[18:19], v[94:95] op_sel_hi:[1,0,1]
	v_pk_fma_f32 v[10:11], v[4:5], v[18:19], v[92:93] op_sel_hi:[1,0,1]
	v_pk_fma_f32 v[4:5], v[2:3], v[18:19], v[90:91] op_sel_hi:[1,0,1]
	v_cvt_pk_bf16_f32 v2, v6, v7
	v_cvt_pk_bf16_f32 v3, v8, v9
	v_cvt_pk_bf16_f32 v4, v4, v5
	v_cvt_pk_bf16_f32 v5, v10, v11
	s_andn2_b64 vcc, exec, s[38:39]
	global_store_dwordx4 v[20:21], v[2:5], off offset:256
	s_cbranch_vccnz .LBB0_158
	s_andn2_b64 vcc, exec, s[18:19]
	s_cbranch_vccnz .LBB0_157
	s_barrier
	s_branch .LBB0_157

; __device__ __forceinline__ unsigned pk2(float lo, float hi) { return pg8::cvt_pk_bf16(lo, hi); }
;     __device__ __forceinline__ void operator()(const f32x4 (&acc)[2][2][4][2], const pg8::Unit& u, int wr, int wc, int fr, int fq) const {
;         const int row0 = u.pm * 256 + wr * 64 + fr, col0 = u.pn * 256 + wc * 32 + 8 * fq;
;         const int Rt = rowbase + u.pm * 256;
;         const float* bp = bias + (size_t)(Rt < TL ? (Rt >> 13) : 8) * FF2 + col0;
;         f32x4 bv[2][2];
; #pragma unroll
;         for (int bj = 0; bj < 2; ++bj) { bv[bj][0] = *(const f32x4*)(bp + bj * 128); bv[bj][1] = *(const f32x4*)(bp + bj * 128 + 4); }
; #pragma unroll
;         for (int ai = 0; ai < 2; ++ai)
; #pragma unroll
;             for (int m = 0; m < 4; ++m) { const int r = row0 + ai * 128 + m * 16, Rg = rowbase + r;
;                 const f32x4 q = *(const f32x4*)(stat + (size_t)Rg * 16 + fq * 4);
;                 float ssq = (q[0] + q[1]) + (q[2] + q[3]); ssq += __shfl_xor(ssq, 16); ssq += __shfl_xor(ssq, 32);
;                 const float rstd = rsqrtf(ssq * (1.f / DM) + 1e-6f);
;                 bf16_t* rowp = O + (size_t)r * ldc + col0;
; #pragma unroll
;                 for (int bj = 0; bj < 2; ++bj) { const f32x4 v0 = acc[ai][bj][m][0] * rstd + bv[bj][0], v1 = acc[ai][bj][m][1] * rstd + bv[bj][1];
;                     u32x4 w; w.x = pk2(v0[0], v0[1]); w.y = pk2(v0[2], v0[3]); w.z = pk2(v1[0], v1[1]); w.w = pk2(v1[2], v1[3]);
;                     *(u32x4*)(rowp + bj * 128) = w; } }
.LBB0_1036:
	s_lshl_b32 s10, s40, 8
	v_add_u32_e32 v180, s10, v176
	v_add_u32_e32 v130, s52, v180
	v_ashrrev_i32_e32 v131, 31, v130
	v_lshlrev_b64 v[130:131], 6, v[130:131]
	v_lshl_add_u64 v[130:131], v[152:153], 0, v[130:131]
	v_lshlrev_b32_e32 v194, 6, v176
	v_and_b32_e32 v195, 48, v163
	v_add_u32_e32 v194, v194, v195
	v_add_u32_e32 v194, 0x20010, v194
	ds_read_b128 v[182:185], v194
	ds_read_b128 v[196:199], v194 offset:1024
	ds_read_b128 v[200:203], v194 offset:2048
	ds_read_b128 v[204:207], v194 offset:3072
	ds_read_b128 v[208:211], v194 offset:8192
	ds_read_b128 v[212:215], v194 offset:9216
	ds_read_b128 v[216:219], v194 offset:10240
	ds_read_b128 v[220:223], v194 offset:11264
	s_add_i32 s10, s10, s52
	s_min_i32 s10, s10, 0x10000
	s_ashr_i32 s10, s10, 13
	s_mulk_i32 s10, 0x1600
	s_ashr_i32 s11, s10, 31
	s_lshl_b64 s[10:11], s[10:11], 2
	v_lshl_or_b32 v160, s41, 8, v178
	s_add_u32 s10, s57, s10
	v_ashrrev_i32_e32 v161, 31, v160
	s_addc_u32 s11, s62, s11
	v_lshl_add_u64 v[130:131], v[160:161], 2, s[10:11]
	v_lshlrev_b32_e32 v195, 2, v178
	v_add_u32_e32 v195, 0x24010, v195
	ds_read_b128 v[142:145], v195
	ds_read_b128 v[138:141], v195 offset:16
	ds_read_b128 v[134:137], v195 offset:512
	ds_read_b128 v[130:133], v195 offset:528
	v_and_b32_e32 v186, 64, v228
	v_xor_b32_e32 v181, 16, v228
	v_add_u32_e32 v189, 64, v186
	v_cmp_lt_i32_e32 vcc, v181, v189
	v_xor_b32_e32 v188, 32, v228
	v_or_b32_e32 v192, 16, v180
	v_cndmask_b32_e32 v181, v228, v181, vcc
	v_lshlrev_b32_e32 v181, 2, v181
	v_cmp_lt_i32_e32 vcc, v188, v189
	v_mov_b64_e32 v[158:159], s[22:23]
	v_lshlrev_b64 v[160:161], 1, v[160:161]
	s_mov_b64 s[34:35], -1
	s_waitcnt vmcnt(0) lgkmcnt(0)
	s_barrier
	v_lshlrev_b32_e32 v244, 4, v228
	v_readfirstlane_b32 s98, v163
	v_readfirstlane_b32 s100, v152
	v_readfirstlane_b32 s101, v153
	s_lshl_b32 s98, s98, 5
	s_lshl_b32 s99, s52, 6
	s_lshl_b32 s32, s71, 14
	s_add_i32 s99, s99, s32
	s_add_i32 s99, s99, s98
	s_add_u32 s100, s100, s99
	s_addc_u32 s101, s101, 0
	s_add_i32 m0, s98, 0x20010
	s_nop 0
	global_load_lds_dwordx4 v244, s[100:101]
	global_load_lds_dwordx4 v244, s[100:101] offset:1024
	s_lshl_b32 s99, s71, 8
	s_add_i32 s99, s99, s52
	s_min_i32 s99, s99, 0x10000
	s_ashr_i32 s99, s99, 13
	s_mulk_i32 s99, 0x1600
	s_lshl_b32 s99, s99, 2
	s_lshl_b32 s32, s73, 10
	s_add_i32 s99, s99, s32
	s_add_u32 s100, s57, s99
	s_addc_u32 s101, s62, 0
	s_mov_b32 m0, 0x24010
	s_nop 0
	global_load_lds_dwordx4 v244, s[100:101]
	v_mov_b32_e32 v186, v183
	v_mov_b32_e32 v187, v184
	v_mov_b32_e32 v183, v185
	v_pk_add_f32 v[182:183], v[186:187], v[182:183]
	v_mad_i64_i32 v[184:185], s[10:11], v180, s92, v[158:159]
	v_add_f32_e32 v183, v182, v183
	v_mov_b32_e32 v186, v183
	s_nop 1
	v_permlane16_swap_b32_e32 v183, v186
	v_cndmask_b32_e32 v182, v228, v188, vcc
	v_lshlrev_b32_e32 v182, 2, v182
	v_lshl_add_u64 v[184:185], v[184:185], 0, v[160:161]
	s_waitcnt lgkmcnt(0)
	v_add_f32_e32 v183, v183, v186
	v_mov_b32_e32 v187, v183
	s_nop 1
	v_permlane32_swap_b32_e32 v183, v187
	v_add_u32_e32 v186, s52, v192
	s_waitcnt lgkmcnt(0)
	v_add_f32_e32 v183, v183, v187
	v_fmamk_f32 v183, v183, 0x3a800000, v162
	v_mul_f32_e32 v187, 0x4b800000, v183
	v_cmp_gt_f32_e32 vcc, s82, v183
	s_nop 1
	v_cndmask_b32_e32 v183, v183, v187, vcc
	v_rsq_f32_e32 v183, v183
	v_ashrrev_i32_e32 v187, 31, v186
	v_lshlrev_b64 v[186:187], 6, v[186:187]
	v_lshl_add_u64 v[186:187], v[152:153], 0, v[186:187]
	v_mul_f32_e32 v188, 0x45800000, v183
	v_cndmask_b32_e32 v188, v183, v188, vcc
	v_pk_fma_f32 v[128:129], v[128:129], v[188:189], v[144:145] op_sel_hi:[1,0,1]
	v_pk_fma_f32 v[126:127], v[126:127], v[188:189], v[142:143] op_sel_hi:[1,0,1]
	v_pk_fma_f32 v[124:125], v[124:125], v[188:189], v[140:141] op_sel_hi:[1,0,1]
	v_pk_fma_f32 v[122:123], v[122:123], v[188:189], v[138:139] op_sel_hi:[1,0,1]
	v_pk_fma_f32 v[120:121], v[120:121], v[188:189], v[136:137] op_sel_hi:[1,0,1]
	v_pk_fma_f32 v[118:119], v[118:119], v[188:189], v[134:135] op_sel_hi:[1,0,1]
	v_pk_fma_f32 v[190:191], v[116:117], v[188:189], v[132:133] op_sel_hi:[1,0,1]
	v_pk_fma_f32 v[188:189], v[114:115], v[188:189], v[130:131] op_sel_hi:[1,0,1]
	v_cvt_pk_bf16_f32 v114, v126, v127
	v_cvt_pk_bf16_f32 v115, v128, v129
	v_cvt_pk_bf16_f32 v116, v122, v123
	v_cvt_pk_bf16_f32 v117, v124, v125
	v_cvt_pk_bf16_f32 v118, v118, v119
	v_cvt_pk_bf16_f32 v119, v120, v121
	v_cvt_pk_bf16_f32 v120, v188, v189
	v_cvt_pk_bf16_f32 v121, v190, v191
	global_store_dwordx4 v[184:185], v[114:117], off
	global_store_dwordx4 v[184:185], v[118:121], off offset:256
	v_or_b32_e32 v122, 32, v180
	s_nop 1
	v_add_f32_e32 v114, v196, v197
	v_add_f32_e32 v115, v198, v199
	v_add_u32_e32 v116, s52, v122
	v_add_f32_e32 v114, v114, v115
	v_mov_b32_e32 v115, v114
	s_nop 1
	v_permlane16_swap_b32_e32 v114, v115
	s_waitcnt lgkmcnt(0)
	v_add_f32_e32 v117, v114, v115
	v_mov_b32_e32 v118, v117
	s_nop 1
	v_permlane32_swap_b32_e32 v117, v118
	v_mad_i64_i32 v[114:115], s[10:11], v192, s92, v[158:159]
	v_lshl_add_u64 v[114:115], v[114:115], 0, v[160:161]
	s_waitcnt lgkmcnt(0)
; __device__ __forceinline__ unsigned pk2(float lo, float hi) { return pg8::cvt_pk_bf16(lo, hi); }
;     __device__ __forceinline__ void operator()(const f32x4 (&acc)[2][2][4][2], const pg8::Unit& u, int wr, int wc, int fr, int fq) const {
;     ...
;             for (int m = 0; m < 4; ++m) { const int r = row0 + ai * 128 + m * 16, Rg = rowbase + r;
;                 const f32x4 q = *(const f32x4*)(stat + (size_t)Rg * 16 + fq * 4);
;                 float ssq = (q[0] + q[1]) + (q[2] + q[3]); ssq += __shfl_xor(ssq, 16); ssq += __shfl_xor(ssq, 32);
;                 const float rstd = rsqrtf(ssq * (1.f / DM) + 1e-6f);
;                 bf16_t* rowp = O + (size_t)r * ldc + col0;
; #pragma unroll
;                 for (int bj = 0; bj < 2; ++bj) { const f32x4 v0 = acc[ai][bj][m][0] * rstd + bv[bj][0], v1 = acc[ai][bj][m][1] * rstd + bv[bj][1];
;                     u32x4 w; w.x = pk2(v0[0], v0[1]); w.y = pk2(v0[2], v0[3]); w.z = pk2(v1[0], v1[1]); w.w = pk2(v1[2], v1[3]);
;                     *(u32x4*)(rowp + bj * 128) = w; } }
	v_add_f32_e32 v117, v117, v118
	v_fmamk_f32 v117, v117, 0x3a800000, v162
	v_mul_f32_e32 v118, 0x4b800000, v117
	v_cmp_gt_f32_e32 vcc, s82, v117
	s_nop 1
	v_cndmask_b32_e32 v117, v117, v118, vcc
	v_rsq_f32_e32 v118, v117
	v_ashrrev_i32_e32 v117, 31, v116
	v_lshlrev_b64 v[116:117], 6, v[116:117]
	v_lshl_add_u64 v[116:117], v[152:153], 0, v[116:117]
	v_mul_f32_e32 v119, 0x45800000, v118
	v_cndmask_b32_e32 v118, v118, v119, vcc
	v_pk_fma_f32 v[112:113], v[112:113], v[118:119], v[144:145] op_sel_hi:[1,0,1]
	v_pk_fma_f32 v[110:111], v[110:111], v[118:119], v[142:143] op_sel_hi:[1,0,1]
	v_pk_fma_f32 v[108:109], v[108:109], v[118:119], v[140:141] op_sel_hi:[1,0,1]
	v_pk_fma_f32 v[106:107], v[106:107], v[118:119], v[138:139] op_sel_hi:[1,0,1]
	v_pk_fma_f32 v[104:105], v[104:105], v[118:119], v[136:137] op_sel_hi:[1,0,1]
	v_pk_fma_f32 v[102:103], v[102:103], v[118:119], v[134:135] op_sel_hi:[1,0,1]
	v_pk_fma_f32 v[120:121], v[100:101], v[118:119], v[132:133] op_sel_hi:[1,0,1]
	v_pk_fma_f32 v[118:119], v[98:99], v[118:119], v[130:131] op_sel_hi:[1,0,1]
	v_cvt_pk_bf16_f32 v98, v110, v111
	v_cvt_pk_bf16_f32 v99, v112, v113
	v_cvt_pk_bf16_f32 v100, v106, v107
	v_cvt_pk_bf16_f32 v101, v108, v109
	v_cvt_pk_bf16_f32 v102, v102, v103
	v_cvt_pk_bf16_f32 v103, v104, v105
	v_cvt_pk_bf16_f32 v104, v118, v119
	v_cvt_pk_bf16_f32 v105, v120, v121
	global_store_dwordx4 v[114:115], v[98:101], off
	global_store_dwordx4 v[114:115], v[102:105], off offset:256
	v_or_b32_e32 v106, 48, v180
	s_nop 1
	v_add_f32_e32 v98, v200, v201
	v_add_f32_e32 v99, v202, v203
	v_add_u32_e32 v100, s52, v106
	v_add_f32_e32 v98, v98, v99
	v_mov_b32_e32 v99, v98
	s_nop 1
	v_permlane16_swap_b32_e32 v98, v99
	s_waitcnt lgkmcnt(0)
	v_add_f32_e32 v101, v98, v99
	v_mov_b32_e32 v102, v101
	s_nop 1
	v_permlane32_swap_b32_e32 v101, v102
	v_mad_i64_i32 v[98:99], s[10:11], v122, s92, v[158:159]
	v_lshl_add_u64 v[98:99], v[98:99], 0, v[160:161]
	s_waitcnt lgkmcnt(0)
	v_add_f32_e32 v101, v101, v102
	v_fmamk_f32 v101, v101, 0x3a800000, v162
	v_mul_f32_e32 v102, 0x4b800000, v101
	v_cmp_gt_f32_e32 vcc, s82, v101
	s_nop 1
	v_cndmask_b32_e32 v101, v101, v102, vcc
	v_rsq_f32_e32 v102, v101
	v_ashrrev_i32_e32 v101, 31, v100
	v_lshlrev_b64 v[100:101], 6, v[100:101]
	v_lshl_add_u64 v[100:101], v[152:153], 0, v[100:101]
	v_mul_f32_e32 v103, 0x45800000, v102
	v_cndmask_b32_e32 v102, v102, v103, vcc
	v_pk_fma_f32 v[96:97], v[96:97], v[102:103], v[144:145] op_sel_hi:[1,0,1]
	v_pk_fma_f32 v[94:95], v[94:95], v[102:103], v[142:143] op_sel_hi:[1,0,1]
	v_pk_fma_f32 v[92:93], v[92:93], v[102:103], v[140:141] op_sel_hi:[1,0,1]
	v_pk_fma_f32 v[90:91], v[90:91], v[102:103], v[138:139] op_sel_hi:[1,0,1]
	v_pk_fma_f32 v[88:89], v[88:89], v[102:103], v[136:137] op_sel_hi:[1,0,1]
	v_pk_fma_f32 v[86:87], v[86:87], v[102:103], v[134:135] op_sel_hi:[1,0,1]
	v_pk_fma_f32 v[104:105], v[84:85], v[102:103], v[132:133] op_sel_hi:[1,0,1]
	v_pk_fma_f32 v[102:103], v[82:83], v[102:103], v[130:131] op_sel_hi:[1,0,1]
	v_cvt_pk_bf16_f32 v82, v94, v95
	v_cvt_pk_bf16_f32 v83, v96, v97
	v_cvt_pk_bf16_f32 v84, v90, v91
	v_cvt_pk_bf16_f32 v85, v92, v93
	v_cvt_pk_bf16_f32 v86, v86, v87
	v_cvt_pk_bf16_f32 v87, v88, v89
	v_cvt_pk_bf16_f32 v88, v102, v103
	v_cvt_pk_bf16_f32 v89, v104, v105
	global_store_dwordx4 v[98:99], v[82:85], off
	global_store_dwordx4 v[98:99], v[86:89], off offset:256
	v_add_u32_e32 v90, 0x80, v180
	s_nop 1
	v_add_f32_e32 v82, v204, v205
	v_add_f32_e32 v83, v206, v207
	v_add_u32_e32 v84, s52, v90
	v_add_f32_e32 v82, v82, v83
	v_mov_b32_e32 v83, v82
	s_nop 1
	v_permlane16_swap_b32_e32 v82, v83
	s_waitcnt lgkmcnt(0)
	v_add_f32_e32 v85, v82, v83
	v_mov_b32_e32 v86, v85
	s_nop 1
	v_permlane32_swap_b32_e32 v85, v86
	v_mad_i64_i32 v[82:83], s[10:11], v106, s92, v[158:159]
	v_lshl_add_u64 v[82:83], v[82:83], 0, v[160:161]
	s_waitcnt lgkmcnt(0)
	v_add_f32_e32 v85, v85, v86
	v_fmamk_f32 v85, v85, 0x3a800000, v162
	v_mul_f32_e32 v86, 0x4b800000, v85
	v_cmp_gt_f32_e32 vcc, s82, v85
	s_nop 1
	v_cndmask_b32_e32 v85, v85, v86, vcc
	v_rsq_f32_e32 v86, v85
	v_ashrrev_i32_e32 v85, 31, v84
	v_lshlrev_b64 v[84:85], 6, v[84:85]
	v_lshl_add_u64 v[84:85], v[152:153], 0, v[84:85]
	v_mul_f32_e32 v87, 0x45800000, v86
	v_cndmask_b32_e32 v86, v86, v87, vcc
	v_pk_fma_f32 v[80:81], v[80:81], v[86:87], v[144:145] op_sel_hi:[1,0,1]
	v_pk_fma_f32 v[78:79], v[78:79], v[86:87], v[142:143] op_sel_hi:[1,0,1]
	v_pk_fma_f32 v[76:77], v[76:77], v[86:87], v[140:141] op_sel_hi:[1,0,1]
	v_pk_fma_f32 v[74:75], v[74:75], v[86:87], v[138:139] op_sel_hi:[1,0,1]
	v_pk_fma_f32 v[72:73], v[72:73], v[86:87], v[136:137] op_sel_hi:[1,0,1]
	v_pk_fma_f32 v[70:71], v[70:71], v[86:87], v[134:135] op_sel_hi:[1,0,1]
	v_pk_fma_f32 v[88:89], v[68:69], v[86:87], v[132:133] op_sel_hi:[1,0,1]
	v_pk_fma_f32 v[86:87], v[66:67], v[86:87], v[130:131] op_sel_hi:[1,0,1]
	v_cvt_pk_bf16_f32 v66, v78, v79
	v_cvt_pk_bf16_f32 v67, v80, v81
	v_cvt_pk_bf16_f32 v68, v74, v75
	v_cvt_pk_bf16_f32 v69, v76, v77
	v_cvt_pk_bf16_f32 v70, v70, v71
	v_cvt_pk_bf16_f32 v71, v72, v73
	v_cvt_pk_bf16_f32 v72, v86, v87
	v_cvt_pk_bf16_f32 v73, v88, v89
	global_store_dwordx4 v[82:83], v[66:69], off
	global_store_dwordx4 v[82:83], v[70:73], off offset:256
	v_add_u32_e32 v74, 0x90, v180
	s_nop 1
	v_add_f32_e32 v66, v208, v209
	v_add_f32_e32 v67, v210, v211
	v_add_u32_e32 v68, s52, v74
	v_add_f32_e32 v66, v66, v67
	v_mov_b32_e32 v67, v66
	s_nop 1
	v_permlane16_swap_b32_e32 v66, v67
	s_waitcnt lgkmcnt(0)
	v_add_f32_e32 v69, v66, v67
	v_mov_b32_e32 v70, v69
	s_nop 1
	v_permlane32_swap_b32_e32 v69, v70
	v_mad_i64_i32 v[66:67], s[10:11], v90, s92, v[158:159]
	v_lshl_add_u64 v[66:67], v[66:67], 0, v[160:161]
	s_waitcnt lgkmcnt(0)
; #define PG8_BAR __builtin_amdgcn_s_barrier()
; __device__ __forceinline__ unsigned pk2(float lo, float hi) { return pg8::cvt_pk_bf16(lo, hi); }
; template <class Epi, class Sched, bool ALIGN_EPI = false, bool SP2 = false>
; __device__ __forceinline__ void gemm_phase(PG8_LAS unsigned char* lds, const Gemm g, const Sched& S, const Epi& E) {
;     ...
;         if (!has_next) break;
; #pragma unroll
;         for (int a = 0; a < 2; ++a)
; #pragma unroll
;             for (int b = 0; b < 2; ++b)
; #pragma unroll
;                 for (int m = 0; m < 4; ++m)
; #pragma unroll
;                     for (int n = 0; n < 2; ++n) acc[a][b][m][n] = (f32x4){0.f, 0.f, 0.f, 0.f};
;         cur = nxt; cA = nA; cB = nB; ++ui;
;         if constexpr (ALIGN_EPI) { if (wr == 1) PG8_BAR; }
;     __device__ __forceinline__ void operator()(const f32x4 (&acc)[2][2][4][2], const pg8::Unit& u, int wr, int wc, int fr, int fq) const {
;     ...
;             for (int m = 0; m < 4; ++m) { const int r = row0 + ai * 128 + m * 16, Rg = rowbase + r;
;                 const f32x4 q = *(const f32x4*)(stat + (size_t)Rg * 16 + fq * 4);
;                 float ssq = (q[0] + q[1]) + (q[2] + q[3]); ssq += __shfl_xor(ssq, 16); ssq += __shfl_xor(ssq, 32);
;                 const float rstd = rsqrtf(ssq * (1.f / DM) + 1e-6f);
;                 bf16_t* rowp = O + (size_t)r * ldc + col0;
; #pragma unroll
;                 for (int bj = 0; bj < 2; ++bj) { const f32x4 v0 = acc[ai][bj][m][0] * rstd + bv[bj][0], v1 = acc[ai][bj][m][1] * rstd + bv[bj][1];
;                     u32x4 w; w.x = pk2(v0[0], v0[1]); w.y = pk2(v0[2], v0[3]); w.z = pk2(v1[0], v1[1]); w.w = pk2(v1[2], v1[3]);
;                     *(u32x4*)(rowp + bj * 128) = w; } }
	v_add_f32_e32 v69, v69, v70
	v_fmamk_f32 v69, v69, 0x3a800000, v162
	v_mul_f32_e32 v70, 0x4b800000, v69
	v_cmp_gt_f32_e32 vcc, s82, v69
	s_nop 1
	v_cndmask_b32_e32 v69, v69, v70, vcc
	v_rsq_f32_e32 v70, v69
	v_ashrrev_i32_e32 v69, 31, v68
	v_lshlrev_b64 v[68:69], 6, v[68:69]
	v_lshl_add_u64 v[68:69], v[152:153], 0, v[68:69]
	v_mul_f32_e32 v71, 0x45800000, v70
	v_cndmask_b32_e32 v70, v70, v71, vcc
	v_pk_fma_f32 v[64:65], v[64:65], v[70:71], v[144:145] op_sel_hi:[1,0,1]
	v_pk_fma_f32 v[62:63], v[62:63], v[70:71], v[142:143] op_sel_hi:[1,0,1]
	v_pk_fma_f32 v[60:61], v[60:61], v[70:71], v[140:141] op_sel_hi:[1,0,1]
	v_pk_fma_f32 v[58:59], v[58:59], v[70:71], v[138:139] op_sel_hi:[1,0,1]
	v_pk_fma_f32 v[56:57], v[56:57], v[70:71], v[136:137] op_sel_hi:[1,0,1]
	v_pk_fma_f32 v[54:55], v[54:55], v[70:71], v[134:135] op_sel_hi:[1,0,1]
	v_pk_fma_f32 v[72:73], v[52:53], v[70:71], v[132:133] op_sel_hi:[1,0,1]
	v_pk_fma_f32 v[70:71], v[50:51], v[70:71], v[130:131] op_sel_hi:[1,0,1]
	v_cvt_pk_bf16_f32 v50, v62, v63
	v_cvt_pk_bf16_f32 v51, v64, v65
	v_cvt_pk_bf16_f32 v52, v58, v59
	v_cvt_pk_bf16_f32 v53, v60, v61
	v_cvt_pk_bf16_f32 v54, v54, v55
	v_cvt_pk_bf16_f32 v55, v56, v57
	v_cvt_pk_bf16_f32 v56, v70, v71
	v_cvt_pk_bf16_f32 v57, v72, v73
	global_store_dwordx4 v[66:67], v[50:53], off
	global_store_dwordx4 v[66:67], v[54:57], off offset:256
	v_add_u32_e32 v58, 0xa0, v180
	s_nop 1
	v_add_f32_e32 v50, v212, v213
	v_add_f32_e32 v51, v214, v215
	v_add_u32_e32 v52, s52, v58
	v_add_f32_e32 v50, v50, v51
	v_mov_b32_e32 v51, v50
	s_nop 1
	v_permlane16_swap_b32_e32 v50, v51
	s_waitcnt lgkmcnt(0)
	v_add_f32_e32 v53, v50, v51
	v_mov_b32_e32 v54, v53
	s_nop 1
	v_permlane32_swap_b32_e32 v53, v54
	v_mad_i64_i32 v[50:51], s[10:11], v74, s92, v[158:159]
	v_lshl_add_u64 v[50:51], v[50:51], 0, v[160:161]
	s_waitcnt lgkmcnt(0)
	v_add_f32_e32 v53, v53, v54
	v_fmamk_f32 v53, v53, 0x3a800000, v162
	v_mul_f32_e32 v54, 0x4b800000, v53
	v_cmp_gt_f32_e32 vcc, s82, v53
	s_nop 1
	v_cndmask_b32_e32 v53, v53, v54, vcc
	v_rsq_f32_e32 v54, v53
	v_ashrrev_i32_e32 v53, 31, v52
	v_lshlrev_b64 v[52:53], 6, v[52:53]
	v_lshl_add_u64 v[52:53], v[152:153], 0, v[52:53]
	v_mul_f32_e32 v55, 0x45800000, v54
	v_cndmask_b32_e32 v54, v54, v55, vcc
	v_pk_fma_f32 v[48:49], v[48:49], v[54:55], v[144:145] op_sel_hi:[1,0,1]
	v_pk_fma_f32 v[46:47], v[46:47], v[54:55], v[142:143] op_sel_hi:[1,0,1]
	v_pk_fma_f32 v[44:45], v[44:45], v[54:55], v[140:141] op_sel_hi:[1,0,1]
	v_pk_fma_f32 v[42:43], v[42:43], v[54:55], v[138:139] op_sel_hi:[1,0,1]
	v_pk_fma_f32 v[40:41], v[40:41], v[54:55], v[136:137] op_sel_hi:[1,0,1]
	v_pk_fma_f32 v[38:39], v[38:39], v[54:55], v[134:135] op_sel_hi:[1,0,1]
	v_pk_fma_f32 v[56:57], v[36:37], v[54:55], v[132:133] op_sel_hi:[1,0,1]
	v_pk_fma_f32 v[54:55], v[34:35], v[54:55], v[130:131] op_sel_hi:[1,0,1]
	v_cvt_pk_bf16_f32 v34, v46, v47
	v_cvt_pk_bf16_f32 v35, v48, v49
	v_cvt_pk_bf16_f32 v36, v42, v43
	v_cvt_pk_bf16_f32 v37, v44, v45
	v_cvt_pk_bf16_f32 v38, v38, v39
	v_cvt_pk_bf16_f32 v39, v40, v41
	v_cvt_pk_bf16_f32 v40, v54, v55
	v_cvt_pk_bf16_f32 v41, v56, v57
	global_store_dwordx4 v[50:51], v[34:37], off
	global_store_dwordx4 v[50:51], v[38:41], off offset:256
	v_add_u32_e32 v42, 0xb0, v180
	s_nop 1
	v_add_f32_e32 v34, v216, v217
	v_add_f32_e32 v35, v218, v219
	v_add_u32_e32 v36, s52, v42
	v_add_f32_e32 v34, v34, v35
	v_mov_b32_e32 v35, v34
	s_nop 1
	v_permlane16_swap_b32_e32 v34, v35
	s_waitcnt lgkmcnt(0)
	v_add_f32_e32 v37, v34, v35
	v_mov_b32_e32 v38, v37
	s_nop 1
	v_permlane32_swap_b32_e32 v37, v38
	v_mad_i64_i32 v[34:35], s[10:11], v58, s92, v[158:159]
	v_lshl_add_u64 v[34:35], v[34:35], 0, v[160:161]
	s_waitcnt lgkmcnt(0)
	v_add_f32_e32 v37, v37, v38
	v_fmamk_f32 v37, v37, 0x3a800000, v162
	v_mul_f32_e32 v38, 0x4b800000, v37
	v_cmp_gt_f32_e32 vcc, s82, v37
	s_nop 1
	v_cndmask_b32_e32 v37, v37, v38, vcc
	v_rsq_f32_e32 v38, v37
	v_ashrrev_i32_e32 v37, 31, v36
	v_lshlrev_b64 v[36:37], 6, v[36:37]
	v_lshl_add_u64 v[36:37], v[152:153], 0, v[36:37]
	v_mul_f32_e32 v39, 0x45800000, v38
	v_cndmask_b32_e32 v38, v38, v39, vcc
	v_pk_fma_f32 v[32:33], v[32:33], v[38:39], v[144:145] op_sel_hi:[1,0,1]
	v_pk_fma_f32 v[30:31], v[30:31], v[38:39], v[142:143] op_sel_hi:[1,0,1]
	v_pk_fma_f32 v[28:29], v[28:29], v[38:39], v[140:141] op_sel_hi:[1,0,1]
	v_pk_fma_f32 v[26:27], v[26:27], v[38:39], v[138:139] op_sel_hi:[1,0,1]
	v_pk_fma_f32 v[24:25], v[24:25], v[38:39], v[136:137] op_sel_hi:[1,0,1]
	v_pk_fma_f32 v[22:23], v[22:23], v[38:39], v[134:135] op_sel_hi:[1,0,1]
	v_pk_fma_f32 v[40:41], v[20:21], v[38:39], v[132:133] op_sel_hi:[1,0,1]
	v_pk_fma_f32 v[38:39], v[18:19], v[38:39], v[130:131] op_sel_hi:[1,0,1]
	v_cvt_pk_bf16_f32 v18, v30, v31
	v_cvt_pk_bf16_f32 v19, v32, v33
	v_cvt_pk_bf16_f32 v20, v26, v27
	v_cvt_pk_bf16_f32 v21, v28, v29
	v_cvt_pk_bf16_f32 v22, v22, v23
	v_cvt_pk_bf16_f32 v23, v24, v25
	v_cvt_pk_bf16_f32 v24, v38, v39
	v_cvt_pk_bf16_f32 v25, v40, v41
	global_store_dwordx4 v[34:35], v[18:21], off
	global_store_dwordx4 v[34:35], v[22:25], off offset:256
	s_andn2_b64 vcc, exec, s[38:39]
	s_nop 1
	v_add_f32_e32 v18, v220, v221
	v_add_f32_e32 v19, v222, v223
	s_nop 0
	v_add_f32_e32 v18, v18, v19
	v_mov_b32_e32 v19, v18
	s_nop 1
	v_permlane16_swap_b32_e32 v18, v19
	s_waitcnt lgkmcnt(0)
	v_add_f32_e32 v18, v18, v19
	v_mov_b32_e32 v19, v18
	s_nop 1
	v_permlane32_swap_b32_e32 v18, v19
	s_waitcnt lgkmcnt(0)
	v_add_f32_e32 v18, v18, v19
	v_fmamk_f32 v18, v18, 0x3a800000, v162
	v_mul_f32_e32 v19, 0x4b800000, v18
	v_cmp_gt_f32_e64 s[40:41], s82, v18
	s_nop 1
	v_cndmask_b32_e64 v18, v18, v19, s[40:41]
	v_rsq_f32_e32 v20, v18
	v_mad_i64_i32 v[18:19], s[10:11], v42, s92, v[158:159]
	v_lshl_add_u64 v[18:19], v[18:19], 0, v[160:161]
	v_mul_f32_e32 v21, 0x45800000, v20
	v_cndmask_b32_e64 v20, v20, v21, s[40:41]
	v_pk_fma_f32 v[16:17], v[16:17], v[20:21], v[144:145] op_sel_hi:[1,0,1]
	v_pk_fma_f32 v[14:15], v[14:15], v[20:21], v[142:143] op_sel_hi:[1,0,1]
	v_pk_fma_f32 v[12:13], v[12:13], v[20:21], v[140:141] op_sel_hi:[1,0,1]
	v_pk_fma_f32 v[10:11], v[10:11], v[20:21], v[138:139] op_sel_hi:[1,0,1]
	v_pk_fma_f32 v[8:9], v[8:9], v[20:21], v[136:137] op_sel_hi:[1,0,1]
	v_pk_fma_f32 v[6:7], v[6:7], v[20:21], v[134:135] op_sel_hi:[1,0,1]
	v_pk_fma_f32 v[22:23], v[4:5], v[20:21], v[132:133] op_sel_hi:[1,0,1]
	v_pk_fma_f32 v[20:21], v[2:3], v[20:21], v[130:131] op_sel_hi:[1,0,1]
	v_cvt_pk_bf16_f32 v2, v14, v15
	v_cvt_pk_bf16_f32 v3, v16, v17
	v_cvt_pk_bf16_f32 v4, v10, v11
	v_cvt_pk_bf16_f32 v5, v12, v13
	v_cvt_pk_bf16_f32 v6, v6, v7
	v_cvt_pk_bf16_f32 v7, v8, v9
	v_cvt_pk_bf16_f32 v8, v20, v21
	v_cvt_pk_bf16_f32 v9, v22, v23
	global_store_dwordx4 v[18:19], v[2:5], off
	global_store_dwordx4 v[18:19], v[6:9], off offset:256
	s_cbranch_vccnz .LBB0_1029
	s_andn2_b64 vcc, exec, s[20:21]
	s_cbranch_vccnz .LBB0_1028
	s_barrier
	s_branch .LBB0_1028

; __device__ __forceinline__ unsigned pk2(float lo, float hi) { return pg8::cvt_pk_bf16(lo, hi); }
;     __device__ __forceinline__ void operator()(const f32x4 (&acc)[2][2][4][2], const pg8::Unit& u, int wr, int wc, int fr, int fq) const {
;         const int row0 = u.pm * 256 + wr * 64 + fr, col0 = u.pn * 256 + wc * 32 + 8 * fq;
;         const int Rt = rowbase + u.pm * 256;
;         const float* bp = bias + (size_t)(Rt < TL ? (Rt >> 13) : 8) * FF2 + col0;
;         f32x4 bv[2][2];
; #pragma unroll
;         for (int bj = 0; bj < 2; ++bj) { bv[bj][0] = *(const f32x4*)(bp + bj * 128); bv[bj][1] = *(const f32x4*)(bp + bj * 128 + 4); }
; #pragma unroll
;         for (int ai = 0; ai < 2; ++ai)
; #pragma unroll
;             for (int m = 0; m < 4; ++m) { const int r = row0 + ai * 128 + m * 16, Rg = rowbase + r;
;                 const f32x4 q = *(const f32x4*)(stat + (size_t)Rg * 16 + fq * 4);
;                 float ssq = (q[0] + q[1]) + (q[2] + q[3]); ssq += __shfl_xor(ssq, 16); ssq += __shfl_xor(ssq, 32);
;                 const float rstd = rsqrtf(ssq * (1.f / DM) + 1e-6f);
;                 bf16_t* rowp = O + (size_t)r * ldc + col0;
; #pragma unroll
;                 for (int bj = 0; bj < 2; ++bj) { const f32x4 v0 = acc[ai][bj][m][0] * rstd + bv[bj][0], v1 = acc[ai][bj][m][1] * rstd + bv[bj][1];
;                     u32x4 w; w.x = pk2(v0[0], v0[1]); w.y = pk2(v0[2], v0[3]); w.z = pk2(v1[0], v1[1]); w.w = pk2(v1[2], v1[3]);
;                     *(u32x4*)(rowp + bj * 128) = w; } }
.LBB0_1278:
	s_lshl_b32 s10, s58, 8
	v_add_u32_e32 v176, s10, v178
	v_ashrrev_i32_e32 v177, 31, v176
	v_lshlrev_b64 v[130:131], 6, v[176:177]
	v_lshl_add_u64 v[130:131], v[152:153], 0, v[130:131]
	v_lshlrev_b32_e32 v194, 6, v178
	v_and_b32_e32 v195, 48, v163
	v_add_u32_e32 v194, v194, v195
	v_add_u32_e32 v194, 0x20010, v194
	ds_read_b128 v[158:161], v194
	ds_read_b128 v[196:199], v194 offset:1024
	ds_read_b128 v[200:203], v194 offset:2048
	ds_read_b128 v[204:207], v194 offset:3072
	ds_read_b128 v[208:211], v194 offset:8192
	ds_read_b128 v[212:215], v194 offset:9216
	ds_read_b128 v[216:219], v194 offset:10240
	ds_read_b128 v[220:223], v194 offset:11264
	s_min_i32 s10, s10, 0x10000
	s_ashr_i32 s10, s10, 13
	s_mulk_i32 s10, 0x1600
	s_ashr_i32 s11, s10, 31
	s_lshl_b64 s[10:11], s[10:11], 2
	v_lshl_or_b32 v184, s57, 8, v180
	s_add_u32 s10, s8, s10
	v_ashrrev_i32_e32 v185, 31, v184
	s_addc_u32 s11, s9, s11
	v_lshl_add_u64 v[130:131], v[184:185], 2, s[10:11]
	v_lshlrev_b32_e32 v195, 2, v180
	v_add_u32_e32 v195, 0x24010, v195
	ds_read_b128 v[142:145], v195
	ds_read_b128 v[138:141], v195 offset:16
	ds_read_b128 v[134:137], v195 offset:512
	ds_read_b128 v[130:133], v195 offset:528
	v_and_b32_e32 v182, 64, v228
	v_xor_b32_e32 v177, 16, v228
	v_add_u32_e32 v187, 64, v182
	v_cmp_lt_i32_e32 vcc, v177, v187
	v_xor_b32_e32 v186, 32, v228
	s_mov_b64 s[34:35], -1
	v_cndmask_b32_e32 v177, v228, v177, vcc
	v_lshlrev_b32_e32 v177, 2, v177
	v_cmp_lt_i32_e32 vcc, v186, v187
	s_waitcnt vmcnt(0) lgkmcnt(0)
	s_barrier
	v_lshlrev_b32_e32 v244, 4, v228
	v_readfirstlane_b32 s98, v163
	v_readfirstlane_b32 s100, v152
	v_readfirstlane_b32 s101, v153
	s_lshl_b32 s98, s98, 5
	s_lshl_b32 s99, 0, 6
	s_lshl_b32 s32, s71, 14
	s_add_i32 s99, s99, s32
	s_add_i32 s99, s99, s98
	s_add_u32 s100, s100, s99
	s_addc_u32 s101, s101, 0
	s_add_i32 m0, s98, 0x20010
	s_nop 0
	global_load_lds_dwordx4 v244, s[100:101]
	global_load_lds_dwordx4 v244, s[100:101] offset:1024
	s_lshl_b32 s99, s71, 8
	s_add_i32 s99, s99, 0
	s_min_i32 s99, s99, 0x10000
	s_ashr_i32 s99, s99, 13
	s_mulk_i32 s99, 0x1600
	s_lshl_b32 s99, s99, 2
	s_lshl_b32 s32, s72, 10
	s_add_i32 s99, s99, s32
	s_add_u32 s100, s8, s99
	s_addc_u32 s101, s9, 0
	s_mov_b32 m0, 0x24010
	s_nop 0
	global_load_lds_dwordx4 v244, s[100:101]
	v_mov_b32_e32 v182, v159
	v_mov_b32_e32 v183, v160
	v_mov_b32_e32 v159, v161
	v_pk_add_f32 v[158:159], v[182:183], v[158:159]
	v_cndmask_b32_e32 v182, v228, v186, vcc
	v_add_f32_e32 v160, v158, v159
	v_mov_b32_e32 v161, v160
	s_nop 1
	v_permlane16_swap_b32_e32 v160, v161
	v_lshlrev_b32_e32 v182, 2, v182
	v_mov_b64_e32 v[158:159], s[22:23]
	v_mad_i64_i32 v[186:187], s[10:11], v176, s83, v[158:159]
	s_waitcnt lgkmcnt(0)
	v_add_f32_e32 v183, v160, v161
	v_mov_b32_e32 v188, v183
	s_nop 1
	v_permlane32_swap_b32_e32 v183, v188
	v_lshlrev_b64 v[160:161], 1, v[184:185]
	v_or_b32_e32 v184, 16, v176
	v_lshl_add_u64 v[186:187], v[186:187], 0, v[160:161]
	s_waitcnt lgkmcnt(0)
	v_add_f32_e32 v183, v183, v188
	v_fmamk_f32 v183, v183, 0x3a800000, v162
	v_mul_f32_e32 v185, 0x4b800000, v183
	v_cmp_gt_f32_e32 vcc, s82, v183
	s_nop 1
	v_cndmask_b32_e32 v183, v183, v185, vcc
	v_rsq_f32_e32 v183, v183
	v_ashrrev_i32_e32 v185, 31, v184
	v_lshlrev_b64 v[188:189], 6, v[184:185]
	v_lshl_add_u64 v[188:189], v[152:153], 0, v[188:189]
	v_mul_f32_e32 v185, 0x45800000, v183
	v_cndmask_b32_e32 v190, v183, v185, vcc
	v_pk_fma_f32 v[128:129], v[128:129], v[190:191], v[144:145] op_sel_hi:[1,0,1]
	v_pk_fma_f32 v[126:127], v[126:127], v[190:191], v[142:143] op_sel_hi:[1,0,1]
	v_pk_fma_f32 v[124:125], v[124:125], v[190:191], v[140:141] op_sel_hi:[1,0,1]
	v_pk_fma_f32 v[122:123], v[122:123], v[190:191], v[138:139] op_sel_hi:[1,0,1]
	v_pk_fma_f32 v[120:121], v[120:121], v[190:191], v[136:137] op_sel_hi:[1,0,1]
	v_pk_fma_f32 v[118:119], v[118:119], v[190:191], v[134:135] op_sel_hi:[1,0,1]
	v_pk_fma_f32 v[192:193], v[116:117], v[190:191], v[132:133] op_sel_hi:[1,0,1]
	v_pk_fma_f32 v[190:191], v[114:115], v[190:191], v[130:131] op_sel_hi:[1,0,1]
	v_cvt_pk_bf16_f32 v114, v126, v127
	v_cvt_pk_bf16_f32 v115, v128, v129
	v_cvt_pk_bf16_f32 v116, v122, v123
	v_cvt_pk_bf16_f32 v117, v124, v125
	v_cvt_pk_bf16_f32 v118, v118, v119
	v_cvt_pk_bf16_f32 v119, v120, v121
	v_cvt_pk_bf16_f32 v120, v190, v191
	v_cvt_pk_bf16_f32 v121, v192, v193
	global_store_dwordx4 v[186:187], v[114:117], off
	global_store_dwordx4 v[186:187], v[118:121], off offset:256
	s_nop 1
	v_add_f32_e32 v114, v196, v197
	v_add_f32_e32 v115, v198, v199
	v_mad_i64_i32 v[116:117], s[10:11], v184, s83, v[158:159]
	v_add_f32_e32 v114, v114, v115
	v_mov_b32_e32 v115, v114
	s_nop 1
	v_permlane16_swap_b32_e32 v114, v115
	v_lshl_add_u64 v[116:117], v[116:117], 0, v[160:161]
	s_waitcnt lgkmcnt(0)
	v_add_f32_e32 v118, v114, v115
	v_mov_b32_e32 v119, v118
	s_nop 1
	v_permlane32_swap_b32_e32 v118, v119
	v_or_b32_e32 v114, 32, v176
	v_ashrrev_i32_e32 v115, 31, v114
	s_waitcnt lgkmcnt(0)
; __device__ __forceinline__ unsigned pk2(float lo, float hi) { return pg8::cvt_pk_bf16(lo, hi); }
;     __device__ __forceinline__ void operator()(const f32x4 (&acc)[2][2][4][2], const pg8::Unit& u, int wr, int wc, int fr, int fq) const {
;     ...
;             for (int m = 0; m < 4; ++m) { const int r = row0 + ai * 128 + m * 16, Rg = rowbase + r;
;                 const f32x4 q = *(const f32x4*)(stat + (size_t)Rg * 16 + fq * 4);
;                 float ssq = (q[0] + q[1]) + (q[2] + q[3]); ssq += __shfl_xor(ssq, 16); ssq += __shfl_xor(ssq, 32);
;                 const float rstd = rsqrtf(ssq * (1.f / DM) + 1e-6f);
;                 bf16_t* rowp = O + (size_t)r * ldc + col0;
; #pragma unroll
;                 for (int bj = 0; bj < 2; ++bj) { const f32x4 v0 = acc[ai][bj][m][0] * rstd + bv[bj][0], v1 = acc[ai][bj][m][1] * rstd + bv[bj][1];
;                     u32x4 w; w.x = pk2(v0[0], v0[1]); w.y = pk2(v0[2], v0[3]); w.z = pk2(v1[0], v1[1]); w.w = pk2(v1[2], v1[3]);
;                     *(u32x4*)(rowp + bj * 128) = w; } }
	v_add_f32_e32 v118, v118, v119
	v_fmamk_f32 v118, v118, 0x3a800000, v162
	v_mul_f32_e32 v119, 0x4b800000, v118
	v_cmp_gt_f32_e32 vcc, s82, v118
	s_nop 1
	v_cndmask_b32_e32 v118, v118, v119, vcc
	v_rsq_f32_e32 v120, v118
	v_lshlrev_b64 v[118:119], 6, v[114:115]
	v_lshl_add_u64 v[118:119], v[152:153], 0, v[118:119]
	v_mul_f32_e32 v115, 0x45800000, v120
	v_cndmask_b32_e32 v120, v120, v115, vcc
	v_pk_fma_f32 v[112:113], v[112:113], v[120:121], v[144:145] op_sel_hi:[1,0,1]
	v_pk_fma_f32 v[110:111], v[110:111], v[120:121], v[142:143] op_sel_hi:[1,0,1]
	v_pk_fma_f32 v[108:109], v[108:109], v[120:121], v[140:141] op_sel_hi:[1,0,1]
	v_pk_fma_f32 v[106:107], v[106:107], v[120:121], v[138:139] op_sel_hi:[1,0,1]
	v_pk_fma_f32 v[104:105], v[104:105], v[120:121], v[136:137] op_sel_hi:[1,0,1]
	v_pk_fma_f32 v[102:103], v[102:103], v[120:121], v[134:135] op_sel_hi:[1,0,1]
	v_pk_fma_f32 v[122:123], v[100:101], v[120:121], v[132:133] op_sel_hi:[1,0,1]
	v_pk_fma_f32 v[120:121], v[98:99], v[120:121], v[130:131] op_sel_hi:[1,0,1]
	v_cvt_pk_bf16_f32 v98, v110, v111
	v_cvt_pk_bf16_f32 v99, v112, v113
	v_cvt_pk_bf16_f32 v100, v106, v107
	v_cvt_pk_bf16_f32 v101, v108, v109
	v_cvt_pk_bf16_f32 v102, v102, v103
	v_cvt_pk_bf16_f32 v103, v104, v105
	v_cvt_pk_bf16_f32 v104, v120, v121
	v_cvt_pk_bf16_f32 v105, v122, v123
	global_store_dwordx4 v[116:117], v[98:101], off
	global_store_dwordx4 v[116:117], v[102:105], off offset:256
	s_nop 1
	v_add_f32_e32 v98, v200, v201
	v_add_f32_e32 v99, v202, v203
	v_mad_i64_i32 v[100:101], s[10:11], v114, s83, v[158:159]
	v_add_f32_e32 v98, v98, v99
	v_mov_b32_e32 v99, v98
	s_nop 1
	v_permlane16_swap_b32_e32 v98, v99
	v_lshl_add_u64 v[100:101], v[100:101], 0, v[160:161]
	s_waitcnt lgkmcnt(0)
	v_add_f32_e32 v102, v98, v99
	v_mov_b32_e32 v103, v102
	s_nop 1
	v_permlane32_swap_b32_e32 v102, v103
	v_or_b32_e32 v98, 48, v176
	v_ashrrev_i32_e32 v99, 31, v98
	s_waitcnt lgkmcnt(0)
	v_add_f32_e32 v102, v102, v103
	v_fmamk_f32 v102, v102, 0x3a800000, v162
	v_mul_f32_e32 v103, 0x4b800000, v102
	v_cmp_gt_f32_e32 vcc, s82, v102
	s_nop 1
	v_cndmask_b32_e32 v102, v102, v103, vcc
	v_rsq_f32_e32 v104, v102
	v_lshlrev_b64 v[102:103], 6, v[98:99]
	v_lshl_add_u64 v[102:103], v[152:153], 0, v[102:103]
	v_mul_f32_e32 v99, 0x45800000, v104
	v_cndmask_b32_e32 v104, v104, v99, vcc
	v_pk_fma_f32 v[96:97], v[96:97], v[104:105], v[144:145] op_sel_hi:[1,0,1]
	v_pk_fma_f32 v[94:95], v[94:95], v[104:105], v[142:143] op_sel_hi:[1,0,1]
	v_pk_fma_f32 v[92:93], v[92:93], v[104:105], v[140:141] op_sel_hi:[1,0,1]
	v_pk_fma_f32 v[90:91], v[90:91], v[104:105], v[138:139] op_sel_hi:[1,0,1]
	v_pk_fma_f32 v[88:89], v[88:89], v[104:105], v[136:137] op_sel_hi:[1,0,1]
	v_pk_fma_f32 v[86:87], v[86:87], v[104:105], v[134:135] op_sel_hi:[1,0,1]
	v_pk_fma_f32 v[106:107], v[84:85], v[104:105], v[132:133] op_sel_hi:[1,0,1]
	v_pk_fma_f32 v[104:105], v[82:83], v[104:105], v[130:131] op_sel_hi:[1,0,1]
	v_cvt_pk_bf16_f32 v82, v94, v95
	v_cvt_pk_bf16_f32 v83, v96, v97
	v_cvt_pk_bf16_f32 v84, v90, v91
	v_cvt_pk_bf16_f32 v85, v92, v93
	v_cvt_pk_bf16_f32 v86, v86, v87
	v_cvt_pk_bf16_f32 v87, v88, v89
	v_cvt_pk_bf16_f32 v88, v104, v105
	v_cvt_pk_bf16_f32 v89, v106, v107
	global_store_dwordx4 v[100:101], v[82:85], off
	global_store_dwordx4 v[100:101], v[86:89], off offset:256
	s_nop 1
	v_add_f32_e32 v82, v204, v205
	v_add_f32_e32 v83, v206, v207
	v_mad_i64_i32 v[84:85], s[10:11], v98, s83, v[158:159]
	v_add_f32_e32 v82, v82, v83
	v_mov_b32_e32 v83, v82
	s_nop 1
	v_permlane16_swap_b32_e32 v82, v83
	v_lshl_add_u64 v[84:85], v[84:85], 0, v[160:161]
	s_waitcnt lgkmcnt(0)
	v_add_f32_e32 v86, v82, v83
	v_mov_b32_e32 v87, v86
	s_nop 1
	v_permlane32_swap_b32_e32 v86, v87
	v_add_u32_e32 v82, 0x80, v176
	v_ashrrev_i32_e32 v83, 31, v82
	s_waitcnt lgkmcnt(0)
	v_add_f32_e32 v86, v86, v87
	v_fmamk_f32 v86, v86, 0x3a800000, v162
	v_mul_f32_e32 v87, 0x4b800000, v86
	v_cmp_gt_f32_e32 vcc, s82, v86
	s_nop 1
	v_cndmask_b32_e32 v86, v86, v87, vcc
	v_rsq_f32_e32 v88, v86
	v_lshlrev_b64 v[86:87], 6, v[82:83]
	v_lshl_add_u64 v[86:87], v[152:153], 0, v[86:87]
	v_mul_f32_e32 v83, 0x45800000, v88
	v_cndmask_b32_e32 v88, v88, v83, vcc
	v_pk_fma_f32 v[80:81], v[80:81], v[88:89], v[144:145] op_sel_hi:[1,0,1]
	v_pk_fma_f32 v[78:79], v[78:79], v[88:89], v[142:143] op_sel_hi:[1,0,1]
	v_pk_fma_f32 v[76:77], v[76:77], v[88:89], v[140:141] op_sel_hi:[1,0,1]
	v_pk_fma_f32 v[74:75], v[74:75], v[88:89], v[138:139] op_sel_hi:[1,0,1]
	v_pk_fma_f32 v[72:73], v[72:73], v[88:89], v[136:137] op_sel_hi:[1,0,1]
	v_pk_fma_f32 v[70:71], v[70:71], v[88:89], v[134:135] op_sel_hi:[1,0,1]
	v_pk_fma_f32 v[90:91], v[68:69], v[88:89], v[132:133] op_sel_hi:[1,0,1]
	v_pk_fma_f32 v[88:89], v[66:67], v[88:89], v[130:131] op_sel_hi:[1,0,1]
	v_cvt_pk_bf16_f32 v66, v78, v79
	v_cvt_pk_bf16_f32 v67, v80, v81
	v_cvt_pk_bf16_f32 v68, v74, v75
	v_cvt_pk_bf16_f32 v69, v76, v77
	v_cvt_pk_bf16_f32 v70, v70, v71
	v_cvt_pk_bf16_f32 v71, v72, v73
	v_cvt_pk_bf16_f32 v72, v88, v89
	v_cvt_pk_bf16_f32 v73, v90, v91
	global_store_dwordx4 v[84:85], v[66:69], off
	global_store_dwordx4 v[84:85], v[70:73], off offset:256
	s_nop 1
	v_add_f32_e32 v66, v208, v209
	v_add_f32_e32 v67, v210, v211
	v_mad_i64_i32 v[68:69], s[10:11], v82, s83, v[158:159]
	v_add_f32_e32 v66, v66, v67
	v_mov_b32_e32 v67, v66
	s_nop 1
	v_permlane16_swap_b32_e32 v66, v67
	v_lshl_add_u64 v[68:69], v[68:69], 0, v[160:161]
	s_waitcnt lgkmcnt(0)
	v_add_f32_e32 v70, v66, v67
	v_mov_b32_e32 v71, v70
	s_nop 1
	v_permlane32_swap_b32_e32 v70, v71
	v_add_u32_e32 v66, 0x90, v176
	v_ashrrev_i32_e32 v67, 31, v66
	s_waitcnt lgkmcnt(0)
; #define PG8_BAR __builtin_amdgcn_s_barrier()
; __device__ __forceinline__ unsigned pk2(float lo, float hi) { return pg8::cvt_pk_bf16(lo, hi); }
; template <class Epi, class Sched, bool ALIGN_EPI = false, bool SP2 = false>
; __device__ __forceinline__ void gemm_phase(PG8_LAS unsigned char* lds, const Gemm g, const Sched& S, const Epi& E) {
;     ...
;         if (!has_next) break;
; #pragma unroll
;         for (int a = 0; a < 2; ++a)
; #pragma unroll
;             for (int b = 0; b < 2; ++b)
; #pragma unroll
;                 for (int m = 0; m < 4; ++m)
; #pragma unroll
;                     for (int n = 0; n < 2; ++n) acc[a][b][m][n] = (f32x4){0.f, 0.f, 0.f, 0.f};
;         cur = nxt; cA = nA; cB = nB; ++ui;
;         if constexpr (ALIGN_EPI) { if (wr == 1) PG8_BAR; }
;     __device__ __forceinline__ void operator()(const f32x4 (&acc)[2][2][4][2], const pg8::Unit& u, int wr, int wc, int fr, int fq) const {
;     ...
;             for (int m = 0; m < 4; ++m) { const int r = row0 + ai * 128 + m * 16, Rg = rowbase + r;
;                 const f32x4 q = *(const f32x4*)(stat + (size_t)Rg * 16 + fq * 4);
;                 float ssq = (q[0] + q[1]) + (q[2] + q[3]); ssq += __shfl_xor(ssq, 16); ssq += __shfl_xor(ssq, 32);
;                 const float rstd = rsqrtf(ssq * (1.f / DM) + 1e-6f);
;                 bf16_t* rowp = O + (size_t)r * ldc + col0;
; #pragma unroll
;                 for (int bj = 0; bj < 2; ++bj) { const f32x4 v0 = acc[ai][bj][m][0] * rstd + bv[bj][0], v1 = acc[ai][bj][m][1] * rstd + bv[bj][1];
;                     u32x4 w; w.x = pk2(v0[0], v0[1]); w.y = pk2(v0[2], v0[3]); w.z = pk2(v1[0], v1[1]); w.w = pk2(v1[2], v1[3]);
;                     *(u32x4*)(rowp + bj * 128) = w; } }
	v_add_f32_e32 v70, v70, v71
	v_fmamk_f32 v70, v70, 0x3a800000, v162
	v_mul_f32_e32 v71, 0x4b800000, v70
	v_cmp_gt_f32_e32 vcc, s82, v70
	s_nop 1
	v_cndmask_b32_e32 v70, v70, v71, vcc
	v_rsq_f32_e32 v72, v70
	v_lshlrev_b64 v[70:71], 6, v[66:67]
	v_lshl_add_u64 v[70:71], v[152:153], 0, v[70:71]
	v_mul_f32_e32 v67, 0x45800000, v72
	v_cndmask_b32_e32 v72, v72, v67, vcc
	v_pk_fma_f32 v[64:65], v[64:65], v[72:73], v[144:145] op_sel_hi:[1,0,1]
	v_pk_fma_f32 v[62:63], v[62:63], v[72:73], v[142:143] op_sel_hi:[1,0,1]
	v_pk_fma_f32 v[60:61], v[60:61], v[72:73], v[140:141] op_sel_hi:[1,0,1]
	v_pk_fma_f32 v[58:59], v[58:59], v[72:73], v[138:139] op_sel_hi:[1,0,1]
	v_pk_fma_f32 v[56:57], v[56:57], v[72:73], v[136:137] op_sel_hi:[1,0,1]
	v_pk_fma_f32 v[54:55], v[54:55], v[72:73], v[134:135] op_sel_hi:[1,0,1]
	v_pk_fma_f32 v[74:75], v[52:53], v[72:73], v[132:133] op_sel_hi:[1,0,1]
	v_pk_fma_f32 v[72:73], v[50:51], v[72:73], v[130:131] op_sel_hi:[1,0,1]
	v_cvt_pk_bf16_f32 v50, v62, v63
	v_cvt_pk_bf16_f32 v51, v64, v65
	v_cvt_pk_bf16_f32 v52, v58, v59
	v_cvt_pk_bf16_f32 v53, v60, v61
	v_cvt_pk_bf16_f32 v54, v54, v55
	v_cvt_pk_bf16_f32 v55, v56, v57
	v_cvt_pk_bf16_f32 v56, v72, v73
	v_cvt_pk_bf16_f32 v57, v74, v75
	global_store_dwordx4 v[68:69], v[50:53], off
	global_store_dwordx4 v[68:69], v[54:57], off offset:256
	s_nop 1
	v_add_f32_e32 v50, v212, v213
	v_add_f32_e32 v51, v214, v215
	v_mad_i64_i32 v[52:53], s[10:11], v66, s83, v[158:159]
	v_add_f32_e32 v50, v50, v51
	v_mov_b32_e32 v51, v50
	s_nop 1
	v_permlane16_swap_b32_e32 v50, v51
	v_lshl_add_u64 v[52:53], v[52:53], 0, v[160:161]
	s_waitcnt lgkmcnt(0)
	v_add_f32_e32 v54, v50, v51
	v_mov_b32_e32 v55, v54
	s_nop 1
	v_permlane32_swap_b32_e32 v54, v55
	v_add_u32_e32 v50, 0xa0, v176
	v_ashrrev_i32_e32 v51, 31, v50
	s_waitcnt lgkmcnt(0)
	v_add_f32_e32 v54, v54, v55
	v_fmamk_f32 v54, v54, 0x3a800000, v162
	v_mul_f32_e32 v55, 0x4b800000, v54
	v_cmp_gt_f32_e32 vcc, s82, v54
	s_nop 1
	v_cndmask_b32_e32 v54, v54, v55, vcc
	v_rsq_f32_e32 v56, v54
	v_lshlrev_b64 v[54:55], 6, v[50:51]
	v_lshl_add_u64 v[54:55], v[152:153], 0, v[54:55]
	v_mul_f32_e32 v51, 0x45800000, v56
	v_cndmask_b32_e32 v56, v56, v51, vcc
	v_pk_fma_f32 v[48:49], v[48:49], v[56:57], v[144:145] op_sel_hi:[1,0,1]
	v_pk_fma_f32 v[46:47], v[46:47], v[56:57], v[142:143] op_sel_hi:[1,0,1]
	v_pk_fma_f32 v[44:45], v[44:45], v[56:57], v[140:141] op_sel_hi:[1,0,1]
	v_pk_fma_f32 v[42:43], v[42:43], v[56:57], v[138:139] op_sel_hi:[1,0,1]
	v_pk_fma_f32 v[40:41], v[40:41], v[56:57], v[136:137] op_sel_hi:[1,0,1]
	v_pk_fma_f32 v[38:39], v[38:39], v[56:57], v[134:135] op_sel_hi:[1,0,1]
	v_pk_fma_f32 v[58:59], v[36:37], v[56:57], v[132:133] op_sel_hi:[1,0,1]
	v_pk_fma_f32 v[56:57], v[34:35], v[56:57], v[130:131] op_sel_hi:[1,0,1]
	v_cvt_pk_bf16_f32 v34, v46, v47
	v_cvt_pk_bf16_f32 v35, v48, v49
	v_cvt_pk_bf16_f32 v36, v42, v43
	v_cvt_pk_bf16_f32 v37, v44, v45
	v_cvt_pk_bf16_f32 v38, v38, v39
	v_cvt_pk_bf16_f32 v39, v40, v41
	v_cvt_pk_bf16_f32 v40, v56, v57
	v_cvt_pk_bf16_f32 v41, v58, v59
	global_store_dwordx4 v[52:53], v[34:37], off
	global_store_dwordx4 v[52:53], v[38:41], off offset:256
	s_nop 1
	v_add_f32_e32 v34, v216, v217
	v_add_f32_e32 v35, v218, v219
	v_mad_i64_i32 v[36:37], s[10:11], v50, s83, v[158:159]
	v_add_f32_e32 v34, v34, v35
	v_mov_b32_e32 v35, v34
	s_nop 1
	v_permlane16_swap_b32_e32 v34, v35
	v_lshl_add_u64 v[36:37], v[36:37], 0, v[160:161]
	s_waitcnt lgkmcnt(0)
	v_add_f32_e32 v38, v34, v35
	v_mov_b32_e32 v39, v38
	s_nop 1
	v_permlane32_swap_b32_e32 v38, v39
	v_add_u32_e32 v34, 0xb0, v176
	v_ashrrev_i32_e32 v35, 31, v34
	s_waitcnt lgkmcnt(0)
	v_add_f32_e32 v38, v38, v39
	v_fmamk_f32 v38, v38, 0x3a800000, v162
	v_mul_f32_e32 v39, 0x4b800000, v38
	v_cmp_gt_f32_e32 vcc, s82, v38
	s_nop 1
	v_cndmask_b32_e32 v38, v38, v39, vcc
	v_rsq_f32_e32 v40, v38
	v_lshlrev_b64 v[38:39], 6, v[34:35]
	v_lshl_add_u64 v[38:39], v[152:153], 0, v[38:39]
	v_mul_f32_e32 v35, 0x45800000, v40
	v_cndmask_b32_e32 v40, v40, v35, vcc
	v_pk_fma_f32 v[32:33], v[32:33], v[40:41], v[144:145] op_sel_hi:[1,0,1]
	v_pk_fma_f32 v[30:31], v[30:31], v[40:41], v[142:143] op_sel_hi:[1,0,1]
	v_pk_fma_f32 v[28:29], v[28:29], v[40:41], v[140:141] op_sel_hi:[1,0,1]
	v_pk_fma_f32 v[26:27], v[26:27], v[40:41], v[138:139] op_sel_hi:[1,0,1]
	v_pk_fma_f32 v[24:25], v[24:25], v[40:41], v[136:137] op_sel_hi:[1,0,1]
	v_pk_fma_f32 v[22:23], v[22:23], v[40:41], v[134:135] op_sel_hi:[1,0,1]
	v_pk_fma_f32 v[42:43], v[20:21], v[40:41], v[132:133] op_sel_hi:[1,0,1]
	v_pk_fma_f32 v[40:41], v[18:19], v[40:41], v[130:131] op_sel_hi:[1,0,1]
	v_cvt_pk_bf16_f32 v18, v30, v31
	v_cvt_pk_bf16_f32 v19, v32, v33
	v_cvt_pk_bf16_f32 v20, v26, v27
	v_cvt_pk_bf16_f32 v21, v28, v29
	v_cvt_pk_bf16_f32 v22, v22, v23
	v_cvt_pk_bf16_f32 v23, v24, v25
	v_cvt_pk_bf16_f32 v24, v40, v41
	v_cvt_pk_bf16_f32 v25, v42, v43
	global_store_dwordx4 v[36:37], v[18:21], off
	global_store_dwordx4 v[36:37], v[22:25], off offset:256
	s_andn2_b64 vcc, exec, s[38:39]
	s_nop 1
	v_add_f32_e32 v18, v220, v221
	v_add_f32_e32 v19, v222, v223
	s_nop 0
	v_add_f32_e32 v18, v18, v19
	v_mov_b32_e32 v19, v18
	s_nop 1
	v_permlane16_swap_b32_e32 v18, v19
	s_waitcnt lgkmcnt(0)
	v_add_f32_e32 v18, v18, v19
	v_mov_b32_e32 v19, v18
	s_nop 1
	v_permlane32_swap_b32_e32 v18, v19
	s_waitcnt lgkmcnt(0)
	v_add_f32_e32 v18, v18, v19
	v_fmamk_f32 v18, v18, 0x3a800000, v162
	v_mul_f32_e32 v19, 0x4b800000, v18
	v_cmp_gt_f32_e64 s[40:41], s82, v18
	s_nop 1
	v_cndmask_b32_e64 v18, v18, v19, s[40:41]
	v_rsq_f32_e32 v20, v18
	v_mad_i64_i32 v[18:19], s[10:11], v34, s83, v[158:159]
	v_lshl_add_u64 v[18:19], v[18:19], 0, v[160:161]
	v_mul_f32_e32 v21, 0x45800000, v20
	v_cndmask_b32_e64 v20, v20, v21, s[40:41]
	v_pk_fma_f32 v[16:17], v[16:17], v[20:21], v[144:145] op_sel_hi:[1,0,1]
	v_pk_fma_f32 v[14:15], v[14:15], v[20:21], v[142:143] op_sel_hi:[1,0,1]
	v_pk_fma_f32 v[12:13], v[12:13], v[20:21], v[140:141] op_sel_hi:[1,0,1]
	v_pk_fma_f32 v[10:11], v[10:11], v[20:21], v[138:139] op_sel_hi:[1,0,1]
	v_pk_fma_f32 v[8:9], v[8:9], v[20:21], v[136:137] op_sel_hi:[1,0,1]
	v_pk_fma_f32 v[6:7], v[6:7], v[20:21], v[134:135] op_sel_hi:[1,0,1]
	v_pk_fma_f32 v[22:23], v[4:5], v[20:21], v[132:133] op_sel_hi:[1,0,1]
	v_pk_fma_f32 v[20:21], v[2:3], v[20:21], v[130:131] op_sel_hi:[1,0,1]
	v_cvt_pk_bf16_f32 v2, v14, v15
	v_cvt_pk_bf16_f32 v3, v16, v17
	v_cvt_pk_bf16_f32 v4, v10, v11
	v_cvt_pk_bf16_f32 v5, v12, v13
	v_cvt_pk_bf16_f32 v6, v6, v7
	v_cvt_pk_bf16_f32 v7, v8, v9
	v_cvt_pk_bf16_f32 v8, v20, v21
	v_cvt_pk_bf16_f32 v9, v22, v23
	global_store_dwordx4 v[18:19], v[2:5], off
	global_store_dwordx4 v[18:19], v[6:9], off offset:256
	s_cbranch_vccnz .LBB0_1271
	s_andn2_b64 vcc, exec, s[20:21]
	s_cbranch_vccnz .LBB0_1270
	s_barrier
	s_branch .LBB0_1270
